# row phases: per-channel gains pre-multiplied once per wave (G*GA and (1+sc)*GB), 32 fewer VALU ops per row (f32 re-association)
# speedup vs baseline: 1.0069x; 1.0010x over previous
.LBB0_49:
	s_add_i32 s0, s76, -2
	s_mul_hi_i32 s1, s0, 0x38e38e39
	s_lshr_b32 s4, s1, 31
	s_ashr_i32 s1, s1, 1
	s_add_i32 s6, s1, s4
	s_mul_i32 s1, s6, 9
	s_mov_b32 s4, s6
	s_sub_i32 s20, s0, s1
	v_writelane_b32 v254, s4, 34
	s_add_u32 s0, s84, 0xaeca000
	s_addc_u32 s1, s85, 0
	v_writelane_b32 v254, s5, 35
	v_writelane_b32 v254, s0, 36
	v_readfirstlane_b32 s28, v160
	s_nop 0
	v_writelane_b32 v254, s1, 37
	s_nop 0
	v_readlane_b32 s0, v254, 32
	v_readlane_b32 s1, v254, 33
	v_readlane_b32 s4, v254, 14
	s_lshl_b64 s[0:1], s[0:1], 2
	v_readlane_b32 s18, v254, 28
	v_readlane_b32 s5, v254, 15
	v_readlane_b32 s19, v254, 29
	s_add_u32 s4, s18, s0
	s_addc_u32 s5, s19, s1
	v_readlane_b32 s6, v254, 16
	v_readlane_b32 s7, v254, 17
	v_readlane_b32 s8, v254, 18
	v_readlane_b32 s9, v254, 19
	v_readlane_b32 s10, v254, 20
	v_readlane_b32 s11, v254, 21
	v_readlane_b32 s12, v254, 22
	v_readlane_b32 s13, v254, 23
	v_readlane_b32 s14, v254, 24
	v_readlane_b32 s15, v254, 25
	v_readlane_b32 s16, v254, 26
	v_readlane_b32 s17, v254, 27
	v_writelane_b32 v254, s4, 38
	s_cmp_lt_i32 s20, 4
	s_nop 0
	v_writelane_b32 v254, s5, 39
	v_writelane_b32 v254, s20, 40
	s_mov_b64 s[4:5], -1
	s_cbranch_scc1 .LBB0_214
	v_readlane_b32 s4, v254, 40
	s_cmp_lt_i32 s4, 6
	s_mov_b64 s[4:5], -1
	s_cbranch_scc1 .LBB0_168
	v_readlane_b32 s4, v254, 40
	s_cmp_lt_i32 s4, 7
	s_mov_b64 s[4:5], -1
	s_cbranch_scc1 .LBB0_150
	v_readlane_b32 s4, v254, 40
	s_cmp_lt_i32 s4, 8
	s_mov_b64 s[4:5], -1
	s_cbranch_scc1 .LBB0_101
	v_readlane_b32 s4, v254, 40
	s_cmp_eq_u32 s4, 8
	s_cbranch_scc0 .LBB0_100
	s_cmp_eq_u32 s76, 37
	s_cbranch_scc1 .Lrow2_last
	v_readfirstlane_b32 s0, v160
	v_readlane_b32 s1, v252, 7
	s_lshr_b32 s0, s0, 6
	s_mov_b32 s73, s0
	s_add_i32 s0, s0, s1
	v_readlane_b32 s62, v254, 34
	s_sub_u32 s64, s78, 0x110
	s_subb_u32 s65, s79, 0
	s_load_dwordx2 s[66:67], s[64:65], 0x40
	s_load_dwordx2 s[10:11], s[64:65], 0xf8
	s_lshl_b32 s63, s0, 11
	s_add_u32 s4, s84, 0x167ca000
	s_addc_u32 s5, s85, 0
	s_add_u32 s4, s4, s63
	s_addc_u32 s5, s5, 0
	s_add_u32 s6, s84, 0x112ca000
	s_addc_u32 s7, s85, 0
	s_add_u32 s6, s6, s63
	s_addc_u32 s7, s7, 0
	v_and_b32_e32 v0, 63, v160
	v_lshlrev_b32_e32 v1, 4, v0
	v_lshlrev_b32_e32 v0, 3, v0
	v_add_u32_e32 v2, 0x400000, v0
	v_add_u32_e32 v3, 0x800000, v0
	v_add_u32_e32 v4, 0xc00000, v0
	v_add_u32_e32 v5, 0x1000000, v0
	global_load_dwordx2 v[8:9], v5, s[6:7] offset:0 nt
	global_load_dwordx2 v[10:11], v5, s[6:7] offset:512 nt
	global_load_dwordx2 v[12:13], v5, s[6:7] offset:1024 nt
	global_load_dwordx2 v[14:15], v5, s[6:7] offset:1536 nt
	global_load_dwordx2 v[16:17], v5, s[4:5] offset:0 nt
	global_load_dwordx2 v[18:19], v5, s[4:5] offset:512 nt
	global_load_dwordx2 v[20:21], v5, s[4:5] offset:1024 nt
	global_load_dwordx2 v[22:23], v5, s[4:5] offset:1536 nt
	s_add_u32 s8, s84, 0xaeca000
	s_addc_u32 s9, s85, 0
	s_add_u32 s8, s8, s63
	s_addc_u32 s9, s9, 0
	s_lshr_b32 s69, s0, 10
	s_add_i32 s69, s69, 1
	s_mul_i32 s69, s69, 0x6000
	s_mul_i32 s68, s62, 0x12000
	s_add_i32 s70, s62, 1
	s_mul_i32 s71, s70, 0x12000
	s_lshl_b32 s70, s70, 14
	s_lshl_b32 s72, s62, 14
	s_add_i32 s72, s72, 0x3000
	s_add_u32 s16, s84, 0x6605000
	s_addc_u32 s17, s85, 0
	s_add_u32 s16, s16, s68
	s_addc_u32 s17, s17, 0
	s_add_u32 s20, s84, 0x6600000
	s_addc_u32 s21, s85, 0
	s_add_u32 s20, s20, s71
	s_addc_u32 s21, s21, 0
	s_add_u32 s18, s20, 0x1000
	s_addc_u32 s19, s21, 0
	s_add_u32 s22, s16, s69
	s_addc_u32 s23, s17, 0
	s_add_u32 s60, s20, s69
	s_addc_u32 s61, s21, 0
	s_add_u32 s26, s18, s69
	s_addc_u32 s27, s19, 0
	s_lshl_b32 s63, s63, 1
	s_waitcnt lgkmcnt(0)
	s_add_u32 s12, s66, s72
	s_addc_u32 s13, s67, 0
	s_add_u32 s14, s66, s70
	s_addc_u32 s15, s67, 0
	s_add_u32 s10, s10, s63
	s_addc_u32 s11, s11, 0
	s_mov_b64 s[74:75], s[12:13]
	s_cmp_eq_u32 s73, 1
	s_cselect_b32 s74, s14, s74
	s_cselect_b32 s75, s15, s75
	s_cmp_eq_u32 s73, 2
	s_cselect_b32 s74, s16, s74
	s_cselect_b32 s75, s17, s75
	s_cmp_eq_u32 s73, 3
	s_cselect_b32 s74, s18, s74
	s_cselect_b32 s75, s19, s75
	s_cmp_eq_u32 s73, 4
	s_cselect_b32 s74, s20, s74
	s_cselect_b32 s75, s21, s75
	s_cmp_eq_u32 s73, 5
	s_cselect_b32 s74, s22, s74
	s_cselect_b32 s75, s23, s75
	s_cmp_eq_u32 s73, 6
	s_cselect_b32 s74, s26, s74
	s_cselect_b32 s75, s27, s75
	s_cmp_eq_u32 s73, 7
	s_cselect_b32 s74, s60, s74
	s_cselect_b32 s75, s61, s75
	global_load_dwordx4 v[222:225], v1, s[74:75] offset:0
	global_load_dwordx4 v[226:229], v1, s[74:75] offset:1024
	global_load_dwordx4 v[230:233], v1, s[74:75] offset:2048
	global_load_dwordx4 v[234:237], v1, s[74:75] offset:3072
	s_lshl_b32 s74, s73, 12
	v_add_u32_e32 v6, s74, v1
	global_load_dwordx2 v[24:25], v0, s[6:7] offset:0 nt
	global_load_dwordx2 v[26:27], v0, s[6:7] offset:512 nt
	global_load_dwordx2 v[28:29], v0, s[6:7] offset:1024 nt
	global_load_dwordx2 v[30:31], v0, s[6:7] offset:1536 nt
	global_load_dwordx2 v[32:33], v0, s[4:5] offset:0 nt
	global_load_dwordx2 v[34:35], v0, s[4:5] offset:512 nt
	global_load_dwordx2 v[36:37], v0, s[4:5] offset:1024 nt
	global_load_dwordx2 v[38:39], v0, s[4:5] offset:1536 nt
	global_load_dwordx2 v[40:41], v2, s[6:7] offset:0 nt
	global_load_dwordx2 v[42:43], v2, s[6:7] offset:512 nt
	global_load_dwordx2 v[44:45], v2, s[6:7] offset:1024 nt
	global_load_dwordx2 v[46:47], v2, s[6:7] offset:1536 nt
	global_load_dwordx2 v[48:49], v2, s[4:5] offset:0 nt
	global_load_dwordx2 v[50:51], v2, s[4:5] offset:512 nt
	global_load_dwordx2 v[52:53], v2, s[4:5] offset:1024 nt
	global_load_dwordx2 v[54:55], v2, s[4:5] offset:1536 nt
	s_waitcnt vmcnt(16)
	ds_write_b128 v6, v[222:225] offset:0
	ds_write_b128 v6, v[226:229] offset:1024
	ds_write_b128 v6, v[230:233] offset:2048
	ds_write_b128 v6, v[234:237] offset:3072
	s_waitcnt lgkmcnt(0)
	s_barrier
	ds_read_b128 v[56:59], v1 offset:0
	ds_read_b128 v[60:63], v1 offset:1024
	ds_read_b128 v[64:67], v1 offset:2048
	ds_read_b128 v[68:71], v1 offset:3072
	ds_read_b128 v[72:75], v1 offset:4096
	ds_read_b128 v[76:79], v1 offset:5120
	ds_read_b128 v[80:83], v1 offset:6144
	ds_read_b128 v[84:87], v1 offset:7168
	ds_read_b128 v[88:91], v1 offset:8192
	ds_read_b128 v[92:95], v1 offset:9216
	ds_read_b128 v[96:99], v1 offset:10240
	ds_read_b128 v[100:103], v1 offset:11264
	ds_read_b128 v[104:107], v1 offset:12288
	ds_read_b128 v[108:111], v1 offset:13312
	ds_read_b128 v[112:115], v1 offset:14336
	ds_read_b128 v[116:119], v1 offset:15360
	ds_read_b128 v[134:137], v1 offset:16384
	ds_read_b128 v[138:141], v1 offset:17408
	ds_read_b128 v[142:145], v1 offset:18432
	ds_read_b128 v[146:149], v1 offset:19456
	ds_read_b128 v[190:193], v1 offset:20480
	ds_read_b128 v[194:197], v1 offset:21504
	ds_read_b128 v[198:201], v1 offset:22528
	ds_read_b128 v[202:205], v1 offset:23552
	ds_read_b128 v[206:209], v1 offset:24576
	ds_read_b128 v[210:213], v1 offset:25600
	ds_read_b128 v[214:217], v1 offset:26624
	ds_read_b128 v[218:221], v1 offset:27648
	ds_read_b128 v[222:225], v1 offset:28672
	ds_read_b128 v[226:229], v1 offset:29696
	ds_read_b128 v[230:233], v1 offset:30720
	ds_read_b128 v[234:237], v1 offset:31744
	v_lshlrev_b32_e32 v246, 16, v8
	v_and_b32_e32 v8, 0xffff0000, v8
	v_lshlrev_b32_e32 v247, 16, v9
	v_and_b32_e32 v9, 0xffff0000, v9
	v_lshlrev_b32_e32 v248, 16, v10
	v_and_b32_e32 v10, 0xffff0000, v10
	v_lshlrev_b32_e32 v249, 16, v11
	v_and_b32_e32 v11, 0xffff0000, v11
	v_lshlrev_b32_e32 v250, 16, v12
	v_and_b32_e32 v12, 0xffff0000, v12
	v_lshlrev_b32_e32 v251, 16, v13
	v_and_b32_e32 v13, 0xffff0000, v13
	v_lshlrev_b32_e32 v176, 16, v14
	v_and_b32_e32 v14, 0xffff0000, v14
	v_lshlrev_b32_e32 v177, 16, v15
	v_and_b32_e32 v15, 0xffff0000, v15
	v_mul_f32_e32 v178, v246, v246
	v_fmac_f32_e32 v178, v8, v8
	v_fmac_f32_e32 v178, v247, v247
	v_fmac_f32_e32 v178, v9, v9
	v_fmac_f32_e32 v178, v248, v248
	v_fmac_f32_e32 v178, v10, v10
	v_fmac_f32_e32 v178, v249, v249
	v_fmac_f32_e32 v178, v11, v11
	v_fmac_f32_e32 v178, v250, v250
	v_fmac_f32_e32 v178, v12, v12
	v_fmac_f32_e32 v178, v251, v251
	v_fmac_f32_e32 v178, v13, v13
	v_fmac_f32_e32 v178, v176, v176
	v_fmac_f32_e32 v178, v14, v14
	v_fmac_f32_e32 v178, v177, v177
	v_fmac_f32_e32 v178, v15, v15
	v_lshlrev_b32_e32 v238, 16, v16
	v_and_b32_e32 v16, 0xffff0000, v16
	v_add_f32_dpp v178, v178, v178 quad_perm:[1,0,3,2] row_mask:0xf bank_mask:0xf bound_ctrl:1
	v_lshlrev_b32_e32 v239, 16, v17
	v_and_b32_e32 v17, 0xffff0000, v17
	v_add_f32_dpp v178, v178, v178 quad_perm:[2,3,0,1] row_mask:0xf bank_mask:0xf bound_ctrl:1
	v_lshlrev_b32_e32 v240, 16, v18
	v_and_b32_e32 v18, 0xffff0000, v18
	v_add_f32_dpp v178, v178, v178 row_half_mirror row_mask:0xf bank_mask:0xf bound_ctrl:1
	v_lshlrev_b32_e32 v241, 16, v19
	v_and_b32_e32 v19, 0xffff0000, v19
	v_add_f32_dpp v178, v178, v178 row_mirror row_mask:0xf bank_mask:0xf bound_ctrl:1
	v_lshlrev_b32_e32 v242, 16, v20
	v_and_b32_e32 v20, 0xffff0000, v20
	v_add_f32_dpp v178, v178, v178 row_bcast:15 row_mask:0xa bank_mask:0xf
	v_lshlrev_b32_e32 v243, 16, v21
	v_and_b32_e32 v21, 0xffff0000, v21
	v_add_f32_dpp v178, v178, v178 row_bcast:31 row_mask:0xc bank_mask:0xf
	v_lshlrev_b32_e32 v244, 16, v22
	v_and_b32_e32 v22, 0xffff0000, v22
	v_lshlrev_b32_e32 v245, 16, v23
	v_and_b32_e32 v23, 0xffff0000, v23
	v_readlane_b32 s0, v178, 63
	s_nop 1
	v_mov_b32_e32 v181, s0
	v_fmamk_f32 v181, v181, 0x3a800000, v161
	v_rsq_f32_e32 v179, v181
	s_nop 0
	s_waitcnt lgkmcnt(0)
	v_mul_f32_e32 v190, v190, v56
	v_mul_f32_e32 v191, v191, v57
	v_mul_f32_e32 v192, v192, v58
	v_mul_f32_e32 v193, v193, v59
	v_mul_f32_e32 v194, v194, v60
	v_mul_f32_e32 v195, v195, v61
	v_mul_f32_e32 v196, v196, v62
	v_mul_f32_e32 v197, v197, v63
	v_mul_f32_e32 v198, v198, v64
	v_mul_f32_e32 v199, v199, v65
	v_mul_f32_e32 v200, v200, v66
	v_mul_f32_e32 v201, v201, v67
	v_mul_f32_e32 v202, v202, v68
	v_mul_f32_e32 v203, v203, v69
	v_mul_f32_e32 v204, v204, v70
	v_mul_f32_e32 v205, v205, v71
	v_mul_f32_e32 v88, v88, v56
	v_mul_f32_e32 v89, v89, v57
	v_mul_f32_e32 v90, v90, v58
	v_mul_f32_e32 v91, v91, v59
	v_mul_f32_e32 v92, v92, v60
	v_mul_f32_e32 v93, v93, v61
	v_mul_f32_e32 v94, v94, v62
	v_mul_f32_e32 v95, v95, v63
	v_mul_f32_e32 v96, v96, v64
	v_mul_f32_e32 v97, v97, v65
	v_mul_f32_e32 v98, v98, v66
	v_mul_f32_e32 v99, v99, v67
	v_mul_f32_e32 v100, v100, v68
	v_mul_f32_e32 v101, v101, v69
	v_mul_f32_e32 v102, v102, v70
	v_mul_f32_e32 v103, v103, v71
	v_mul_f32_e32 v246, v246, v179
	v_mul_f32_e32 v8, v8, v179
	v_mul_f32_e32 v247, v247, v179
	v_mul_f32_e32 v9, v9, v179
	v_mul_f32_e32 v248, v248, v179
	v_mul_f32_e32 v10, v10, v179
	v_mul_f32_e32 v249, v249, v179
	v_mul_f32_e32 v11, v11, v179
	v_mul_f32_e32 v250, v250, v179
	v_mul_f32_e32 v12, v12, v179
	v_mul_f32_e32 v251, v251, v179
	v_mul_f32_e32 v13, v13, v179
	v_mul_f32_e32 v176, v176, v179
	v_mul_f32_e32 v14, v14, v179
	v_mul_f32_e32 v177, v177, v179
	v_mul_f32_e32 v15, v15, v179
	v_fmac_f32_e32 v238, v190, v246
	v_fmac_f32_e32 v16, v191, v8
	v_fmac_f32_e32 v239, v192, v247
	v_fmac_f32_e32 v17, v193, v9
	v_fmac_f32_e32 v240, v194, v248
	v_fmac_f32_e32 v18, v195, v10
	v_fmac_f32_e32 v241, v196, v249
	v_fmac_f32_e32 v19, v197, v11
	v_fmac_f32_e32 v242, v198, v250
	v_fmac_f32_e32 v20, v199, v12
	v_fmac_f32_e32 v243, v200, v251
	v_fmac_f32_e32 v21, v201, v13
	v_fmac_f32_e32 v244, v202, v176
	v_fmac_f32_e32 v22, v203, v14
	v_fmac_f32_e32 v245, v204, v177
	v_fmac_f32_e32 v23, v205, v15
	v_cvt_pk_bf16_f32 v120, v238, v16
	v_cvt_pk_bf16_f32 v121, v239, v17
	global_store_dwordx2 v5, v[120:121], s[4:5] offset:0 nt
	v_cvt_pk_bf16_f32 v122, v240, v18
	v_cvt_pk_bf16_f32 v123, v241, v19
	global_store_dwordx2 v5, v[122:123], s[4:5] offset:512 nt
	v_cvt_pk_bf16_f32 v124, v242, v20
	v_cvt_pk_bf16_f32 v125, v243, v21
	global_store_dwordx2 v5, v[124:125], s[4:5] offset:1024 nt
	v_cvt_pk_bf16_f32 v126, v244, v22
	v_cvt_pk_bf16_f32 v127, v245, v23
	global_store_dwordx2 v5, v[126:127], s[4:5] offset:1536 nt
	v_mul_f32_e32 v178, v238, v238
	v_fmac_f32_e32 v178, v16, v16
	v_fmac_f32_e32 v178, v239, v239
	v_fmac_f32_e32 v178, v17, v17
	v_fmac_f32_e32 v178, v240, v240
	v_fmac_f32_e32 v178, v18, v18
	v_fmac_f32_e32 v178, v241, v241
	v_fmac_f32_e32 v178, v19, v19
	v_fmac_f32_e32 v178, v242, v242
	v_fmac_f32_e32 v178, v20, v20
	v_fmac_f32_e32 v178, v243, v243
	v_fmac_f32_e32 v178, v21, v21
	v_fmac_f32_e32 v178, v244, v244
	v_fmac_f32_e32 v178, v22, v22
	v_fmac_f32_e32 v178, v245, v245
	v_fmac_f32_e32 v178, v23, v23
	v_add_f32_e32 v206, 1.0, v206
	v_add_f32_e32 v207, 1.0, v207
	v_add_f32_dpp v178, v178, v178 quad_perm:[1,0,3,2] row_mask:0xf bank_mask:0xf bound_ctrl:1
	v_add_f32_e32 v208, 1.0, v208
	v_add_f32_e32 v209, 1.0, v209
	v_add_f32_dpp v178, v178, v178 quad_perm:[2,3,0,1] row_mask:0xf bank_mask:0xf bound_ctrl:1
	v_add_f32_e32 v210, 1.0, v210
	v_add_f32_e32 v211, 1.0, v211
	v_add_f32_dpp v178, v178, v178 row_half_mirror row_mask:0xf bank_mask:0xf bound_ctrl:1
	v_add_f32_e32 v212, 1.0, v212
	v_add_f32_e32 v213, 1.0, v213
	v_add_f32_dpp v178, v178, v178 row_mirror row_mask:0xf bank_mask:0xf bound_ctrl:1
	v_add_f32_e32 v214, 1.0, v214
	v_add_f32_e32 v215, 1.0, v215
	v_add_f32_dpp v178, v178, v178 row_bcast:15 row_mask:0xa bank_mask:0xf
	v_add_f32_e32 v216, 1.0, v216
	v_add_f32_e32 v217, 1.0, v217
	v_add_f32_dpp v178, v178, v178 row_bcast:31 row_mask:0xc bank_mask:0xf
	v_add_f32_e32 v218, 1.0, v218
	v_add_f32_e32 v219, 1.0, v219
	v_add_f32_e32 v220, 1.0, v220
	v_add_f32_e32 v221, 1.0, v221
	v_mul_f32_e32 v206, v206, v72
	v_mul_f32_e32 v207, v207, v73
	v_mul_f32_e32 v208, v208, v74
	v_mul_f32_e32 v209, v209, v75
	v_mul_f32_e32 v210, v210, v76
	v_mul_f32_e32 v211, v211, v77
	v_mul_f32_e32 v212, v212, v78
	v_mul_f32_e32 v213, v213, v79
	v_mul_f32_e32 v214, v214, v80
	v_mul_f32_e32 v215, v215, v81
	v_mul_f32_e32 v216, v216, v82
	v_mul_f32_e32 v217, v217, v83
	v_mul_f32_e32 v218, v218, v84
	v_mul_f32_e32 v219, v219, v85
	v_mul_f32_e32 v220, v220, v86
	v_mul_f32_e32 v221, v221, v87
	v_readlane_b32 s0, v178, 63
	s_nop 1
	v_mov_b32_e32 v181, s0
	v_fmamk_f32 v181, v181, 0x3a800000, v161
	v_rsq_f32_e32 v180, v181
	s_nop 0
	v_mul_f32_e32 v238, v238, v180
	v_mul_f32_e32 v16, v16, v180
	v_mul_f32_e32 v239, v239, v180
	v_mul_f32_e32 v17, v17, v180
	v_mul_f32_e32 v240, v240, v180
	v_mul_f32_e32 v18, v18, v180
	v_mul_f32_e32 v241, v241, v180
	v_mul_f32_e32 v19, v19, v180
	v_mul_f32_e32 v242, v242, v180
	v_mul_f32_e32 v20, v20, v180
	v_mul_f32_e32 v243, v243, v180
	v_mul_f32_e32 v21, v21, v180
	v_mul_f32_e32 v244, v244, v180
	v_mul_f32_e32 v22, v22, v180
	v_mul_f32_e32 v245, v245, v180
	v_mul_f32_e32 v23, v23, v180
	v_fma_f32 v238, v238, v206, v222
	v_fma_f32 v16, v16, v207, v223
	v_fma_f32 v239, v239, v208, v224
	v_fma_f32 v17, v17, v209, v225
	v_fma_f32 v240, v240, v210, v226
	v_fma_f32 v18, v18, v211, v227
	v_fma_f32 v241, v241, v212, v228
	v_fma_f32 v19, v19, v213, v229
	v_fma_f32 v242, v242, v214, v230
	v_fma_f32 v20, v20, v215, v231
	v_fma_f32 v243, v243, v216, v232
	v_fma_f32 v21, v21, v217, v233
	v_fma_f32 v244, v244, v218, v234
	v_fma_f32 v22, v22, v219, v235
	v_fma_f32 v245, v245, v220, v236
	v_fma_f32 v23, v23, v221, v237
	v_cvt_pk_bf16_f32 v150, v238, v16
	v_cvt_pk_bf16_f32 v151, v239, v17
	global_store_dwordx2 v5, v[150:151], s[8:9] offset:0
	v_cvt_pk_bf16_f32 v152, v240, v18
	v_cvt_pk_bf16_f32 v153, v241, v19
	global_store_dwordx2 v5, v[152:153], s[8:9] offset:512
	v_cvt_pk_bf16_f32 v154, v242, v20
	v_cvt_pk_bf16_f32 v155, v243, v21
	global_store_dwordx2 v5, v[154:155], s[8:9] offset:1024
	v_cvt_pk_bf16_f32 v156, v244, v22
	v_cvt_pk_bf16_f32 v157, v245, v23
	global_store_dwordx2 v5, v[156:157], s[8:9] offset:1536
	global_load_dwordx2 v[8:9], v3, s[6:7] offset:0 nt
	global_load_dwordx2 v[10:11], v3, s[6:7] offset:512 nt
	global_load_dwordx2 v[12:13], v3, s[6:7] offset:1024 nt
	global_load_dwordx2 v[14:15], v3, s[6:7] offset:1536 nt
	global_load_dwordx2 v[16:17], v3, s[4:5] offset:0 nt
	global_load_dwordx2 v[18:19], v3, s[4:5] offset:512 nt
	global_load_dwordx2 v[20:21], v3, s[4:5] offset:1024 nt
	global_load_dwordx2 v[22:23], v3, s[4:5] offset:1536 nt
	global_load_dwordx2 v[190:191], v4, s[6:7] offset:0 nt
	global_load_dwordx2 v[192:193], v4, s[6:7] offset:512 nt
	global_load_dwordx2 v[194:195], v4, s[6:7] offset:1024 nt
	global_load_dwordx2 v[196:197], v4, s[6:7] offset:1536 nt
	global_load_dwordx2 v[198:199], v4, s[4:5] offset:0 nt
	global_load_dwordx2 v[200:201], v4, s[4:5] offset:512 nt
	global_load_dwordx2 v[202:203], v4, s[4:5] offset:1024 nt
	global_load_dwordx2 v[204:205], v4, s[4:5] offset:1536 nt
	s_waitcnt vmcnt(36)
	v_lshlrev_b32_e32 v246, 16, v24
	v_and_b32_e32 v24, 0xffff0000, v24
	v_lshlrev_b32_e32 v247, 16, v25
	v_and_b32_e32 v25, 0xffff0000, v25
	v_lshlrev_b32_e32 v248, 16, v26
	v_and_b32_e32 v26, 0xffff0000, v26
	v_lshlrev_b32_e32 v249, 16, v27
	v_and_b32_e32 v27, 0xffff0000, v27
	v_lshlrev_b32_e32 v250, 16, v28
	v_and_b32_e32 v28, 0xffff0000, v28
	v_lshlrev_b32_e32 v251, 16, v29
	v_and_b32_e32 v29, 0xffff0000, v29
	v_lshlrev_b32_e32 v176, 16, v30
	v_and_b32_e32 v30, 0xffff0000, v30
	v_lshlrev_b32_e32 v177, 16, v31
	v_and_b32_e32 v31, 0xffff0000, v31
	v_mul_f32_e32 v178, v246, v246
	v_fmac_f32_e32 v178, v24, v24
	v_fmac_f32_e32 v178, v247, v247
	v_fmac_f32_e32 v178, v25, v25
	v_fmac_f32_e32 v178, v248, v248
	v_fmac_f32_e32 v178, v26, v26
	v_fmac_f32_e32 v178, v249, v249
	v_fmac_f32_e32 v178, v27, v27
	v_fmac_f32_e32 v178, v250, v250
	v_fmac_f32_e32 v178, v28, v28
	v_fmac_f32_e32 v178, v251, v251
	v_fmac_f32_e32 v178, v29, v29
	v_fmac_f32_e32 v178, v176, v176
	v_fmac_f32_e32 v178, v30, v30
	v_fmac_f32_e32 v178, v177, v177
	v_fmac_f32_e32 v178, v31, v31
	s_waitcnt vmcnt(32)
	v_lshlrev_b32_e32 v238, 16, v32
	v_and_b32_e32 v32, 0xffff0000, v32
	v_add_f32_dpp v178, v178, v178 quad_perm:[1,0,3,2] row_mask:0xf bank_mask:0xf bound_ctrl:1
	v_lshlrev_b32_e32 v239, 16, v33
	v_and_b32_e32 v33, 0xffff0000, v33
	v_add_f32_dpp v178, v178, v178 quad_perm:[2,3,0,1] row_mask:0xf bank_mask:0xf bound_ctrl:1
	v_lshlrev_b32_e32 v240, 16, v34
	v_and_b32_e32 v34, 0xffff0000, v34
	v_add_f32_dpp v178, v178, v178 row_half_mirror row_mask:0xf bank_mask:0xf bound_ctrl:1
	v_lshlrev_b32_e32 v241, 16, v35
	v_and_b32_e32 v35, 0xffff0000, v35
	v_add_f32_dpp v178, v178, v178 row_mirror row_mask:0xf bank_mask:0xf bound_ctrl:1
	v_lshlrev_b32_e32 v242, 16, v36
	v_and_b32_e32 v36, 0xffff0000, v36
	v_add_f32_dpp v178, v178, v178 row_bcast:15 row_mask:0xa bank_mask:0xf
	v_lshlrev_b32_e32 v243, 16, v37
	v_and_b32_e32 v37, 0xffff0000, v37
	v_add_f32_dpp v178, v178, v178 row_bcast:31 row_mask:0xc bank_mask:0xf
	v_lshlrev_b32_e32 v244, 16, v38
	v_and_b32_e32 v38, 0xffff0000, v38
	v_lshlrev_b32_e32 v245, 16, v39
	v_and_b32_e32 v39, 0xffff0000, v39
	v_readlane_b32 s0, v178, 63
	s_nop 1
	v_mov_b32_e32 v181, s0
	v_fmamk_f32 v181, v181, 0x3a800000, v161
	v_rsq_f32_e32 v179, v181
	s_nop 0
	v_mul_f32_e32 v246, v246, v179
	v_mul_f32_e32 v24, v24, v179
	v_mul_f32_e32 v247, v247, v179
	v_mul_f32_e32 v25, v25, v179
	v_mul_f32_e32 v248, v248, v179
	v_mul_f32_e32 v26, v26, v179
	v_mul_f32_e32 v249, v249, v179
	v_mul_f32_e32 v27, v27, v179
	v_mul_f32_e32 v250, v250, v179
	v_mul_f32_e32 v28, v28, v179
	v_mul_f32_e32 v251, v251, v179
	v_mul_f32_e32 v29, v29, v179
	v_mul_f32_e32 v176, v176, v179
	v_mul_f32_e32 v30, v30, v179
	v_mul_f32_e32 v177, v177, v179
	v_mul_f32_e32 v31, v31, v179
	v_fmac_f32_e32 v238, v88, v246
	v_fmac_f32_e32 v32, v89, v24
	v_fmac_f32_e32 v239, v90, v247
	v_fmac_f32_e32 v33, v91, v25
	v_fmac_f32_e32 v240, v92, v248
	v_fmac_f32_e32 v34, v93, v26
	v_fmac_f32_e32 v241, v94, v249
	v_fmac_f32_e32 v35, v95, v27
	v_fmac_f32_e32 v242, v96, v250
	v_fmac_f32_e32 v36, v97, v28
	v_fmac_f32_e32 v243, v98, v251
	v_fmac_f32_e32 v37, v99, v29
	v_fmac_f32_e32 v244, v100, v176
	v_fmac_f32_e32 v38, v101, v30
	v_fmac_f32_e32 v245, v102, v177
	v_fmac_f32_e32 v39, v103, v31
	v_cvt_pk_bf16_f32 v120, v238, v32
	v_cvt_pk_bf16_f32 v121, v239, v33
	global_store_dwordx2 v0, v[120:121], s[4:5] offset:0 nt
	v_cvt_pk_bf16_f32 v122, v240, v34
	v_cvt_pk_bf16_f32 v123, v241, v35
	global_store_dwordx2 v0, v[122:123], s[4:5] offset:512 nt
	v_cvt_pk_bf16_f32 v124, v242, v36
	v_cvt_pk_bf16_f32 v125, v243, v37
	global_store_dwordx2 v0, v[124:125], s[4:5] offset:1024 nt
	v_cvt_pk_bf16_f32 v126, v244, v38
	v_cvt_pk_bf16_f32 v127, v245, v39
	global_store_dwordx2 v0, v[126:127], s[4:5] offset:1536 nt
	v_mul_f32_e32 v178, v238, v238
	v_fmac_f32_e32 v178, v32, v32
	v_fmac_f32_e32 v178, v239, v239
	v_fmac_f32_e32 v178, v33, v33
	v_fmac_f32_e32 v178, v240, v240
	v_fmac_f32_e32 v178, v34, v34
	v_fmac_f32_e32 v178, v241, v241
	v_fmac_f32_e32 v178, v35, v35
	v_fmac_f32_e32 v178, v242, v242
	v_fmac_f32_e32 v178, v36, v36
	v_fmac_f32_e32 v178, v243, v243
	v_fmac_f32_e32 v178, v37, v37
	v_fmac_f32_e32 v178, v244, v244
	v_fmac_f32_e32 v178, v38, v38
	v_fmac_f32_e32 v178, v245, v245
	v_fmac_f32_e32 v178, v39, v39
	v_add_f32_e32 v104, 1.0, v104
	v_add_f32_e32 v105, 1.0, v105
	v_add_f32_dpp v178, v178, v178 quad_perm:[1,0,3,2] row_mask:0xf bank_mask:0xf bound_ctrl:1
	v_add_f32_e32 v106, 1.0, v106
	v_add_f32_e32 v107, 1.0, v107
	v_add_f32_dpp v178, v178, v178 quad_perm:[2,3,0,1] row_mask:0xf bank_mask:0xf bound_ctrl:1
	v_add_f32_e32 v108, 1.0, v108
	v_add_f32_e32 v109, 1.0, v109
	v_add_f32_dpp v178, v178, v178 row_half_mirror row_mask:0xf bank_mask:0xf bound_ctrl:1
	v_add_f32_e32 v110, 1.0, v110
	v_add_f32_e32 v111, 1.0, v111
	v_add_f32_dpp v178, v178, v178 row_mirror row_mask:0xf bank_mask:0xf bound_ctrl:1
	v_add_f32_e32 v112, 1.0, v112
	v_add_f32_e32 v113, 1.0, v113
	v_add_f32_dpp v178, v178, v178 row_bcast:15 row_mask:0xa bank_mask:0xf
	v_add_f32_e32 v114, 1.0, v114
	v_add_f32_e32 v115, 1.0, v115
	v_add_f32_dpp v178, v178, v178 row_bcast:31 row_mask:0xc bank_mask:0xf
	v_add_f32_e32 v116, 1.0, v116
	v_add_f32_e32 v117, 1.0, v117
	v_add_f32_e32 v118, 1.0, v118
	v_add_f32_e32 v119, 1.0, v119
	v_mul_f32_e32 v104, v104, v72
	v_mul_f32_e32 v105, v105, v73
	v_mul_f32_e32 v106, v106, v74
	v_mul_f32_e32 v107, v107, v75
	v_mul_f32_e32 v108, v108, v76
	v_mul_f32_e32 v109, v109, v77
	v_mul_f32_e32 v110, v110, v78
	v_mul_f32_e32 v111, v111, v79
	v_mul_f32_e32 v112, v112, v80
	v_mul_f32_e32 v113, v113, v81
	v_mul_f32_e32 v114, v114, v82
	v_mul_f32_e32 v115, v115, v83
	v_mul_f32_e32 v116, v116, v84
	v_mul_f32_e32 v117, v117, v85
	v_mul_f32_e32 v118, v118, v86
	v_mul_f32_e32 v119, v119, v87
	v_readlane_b32 s0, v178, 63
	s_nop 1
	v_mov_b32_e32 v181, s0
	v_fmamk_f32 v181, v181, 0x3a800000, v161
	v_rsq_f32_e32 v180, v181
	s_nop 0
	v_mul_f32_e32 v238, v238, v180
	v_mul_f32_e32 v32, v32, v180
	v_mul_f32_e32 v239, v239, v180
	v_mul_f32_e32 v33, v33, v180
	v_mul_f32_e32 v240, v240, v180
	v_mul_f32_e32 v34, v34, v180
	v_mul_f32_e32 v241, v241, v180
	v_mul_f32_e32 v35, v35, v180
	v_mul_f32_e32 v242, v242, v180
	v_mul_f32_e32 v36, v36, v180
	v_mul_f32_e32 v243, v243, v180
	v_mul_f32_e32 v37, v37, v180
	v_mul_f32_e32 v244, v244, v180
	v_mul_f32_e32 v38, v38, v180
	v_mul_f32_e32 v245, v245, v180
	v_mul_f32_e32 v39, v39, v180
	v_fma_f32 v238, v238, v104, v134
	v_fma_f32 v32, v32, v105, v135
	v_fma_f32 v239, v239, v106, v136
	v_fma_f32 v33, v33, v107, v137
	v_fma_f32 v240, v240, v108, v138
	v_fma_f32 v34, v34, v109, v139
	v_fma_f32 v241, v241, v110, v140
	v_fma_f32 v35, v35, v111, v141
	v_fma_f32 v242, v242, v112, v142
	v_fma_f32 v36, v36, v113, v143
	v_fma_f32 v243, v243, v114, v144
	v_fma_f32 v37, v37, v115, v145
	v_fma_f32 v244, v244, v116, v146
	v_fma_f32 v38, v38, v117, v147
	v_fma_f32 v245, v245, v118, v148
	v_fma_f32 v39, v39, v119, v149
	v_cvt_pk_bf16_f32 v150, v238, v32
	v_cvt_pk_bf16_f32 v151, v239, v33
	global_store_dwordx2 v0, v[150:151], s[8:9] offset:0
	v_cvt_pk_bf16_f32 v152, v240, v34
	v_cvt_pk_bf16_f32 v153, v241, v35
	global_store_dwordx2 v0, v[152:153], s[8:9] offset:512
	v_cvt_pk_bf16_f32 v154, v242, v36
	v_cvt_pk_bf16_f32 v155, v243, v37
	global_store_dwordx2 v0, v[154:155], s[8:9] offset:1024
	v_cvt_pk_bf16_f32 v156, v244, v38
	v_cvt_pk_bf16_f32 v157, v245, v39
	global_store_dwordx2 v0, v[156:157], s[8:9] offset:1536
	s_waitcnt vmcnt(36)
	v_lshlrev_b32_e32 v246, 16, v40
	v_and_b32_e32 v40, 0xffff0000, v40
	v_lshlrev_b32_e32 v247, 16, v41
	v_and_b32_e32 v41, 0xffff0000, v41
	v_lshlrev_b32_e32 v248, 16, v42
	v_and_b32_e32 v42, 0xffff0000, v42
	v_lshlrev_b32_e32 v249, 16, v43
	v_and_b32_e32 v43, 0xffff0000, v43
	v_lshlrev_b32_e32 v250, 16, v44
	v_and_b32_e32 v44, 0xffff0000, v44
	v_lshlrev_b32_e32 v251, 16, v45
	v_and_b32_e32 v45, 0xffff0000, v45
	v_lshlrev_b32_e32 v176, 16, v46
	v_and_b32_e32 v46, 0xffff0000, v46
	v_lshlrev_b32_e32 v177, 16, v47
	v_and_b32_e32 v47, 0xffff0000, v47
	v_mul_f32_e32 v178, v246, v246
	v_fmac_f32_e32 v178, v40, v40
	v_fmac_f32_e32 v178, v247, v247
	v_fmac_f32_e32 v178, v41, v41
	v_fmac_f32_e32 v178, v248, v248
	v_fmac_f32_e32 v178, v42, v42
	v_fmac_f32_e32 v178, v249, v249
	v_fmac_f32_e32 v178, v43, v43
	v_fmac_f32_e32 v178, v250, v250
	v_fmac_f32_e32 v178, v44, v44
	v_fmac_f32_e32 v178, v251, v251
	v_fmac_f32_e32 v178, v45, v45
	v_fmac_f32_e32 v178, v176, v176
	v_fmac_f32_e32 v178, v46, v46
	v_fmac_f32_e32 v178, v177, v177
	v_fmac_f32_e32 v178, v47, v47
	s_waitcnt vmcnt(32)
	v_lshlrev_b32_e32 v238, 16, v48
	v_and_b32_e32 v48, 0xffff0000, v48
	v_add_f32_dpp v178, v178, v178 quad_perm:[1,0,3,2] row_mask:0xf bank_mask:0xf bound_ctrl:1
	v_lshlrev_b32_e32 v239, 16, v49
	v_and_b32_e32 v49, 0xffff0000, v49
	v_add_f32_dpp v178, v178, v178 quad_perm:[2,3,0,1] row_mask:0xf bank_mask:0xf bound_ctrl:1
	v_lshlrev_b32_e32 v240, 16, v50
	v_and_b32_e32 v50, 0xffff0000, v50
	v_add_f32_dpp v178, v178, v178 row_half_mirror row_mask:0xf bank_mask:0xf bound_ctrl:1
	v_lshlrev_b32_e32 v241, 16, v51
	v_and_b32_e32 v51, 0xffff0000, v51
	v_add_f32_dpp v178, v178, v178 row_mirror row_mask:0xf bank_mask:0xf bound_ctrl:1
	v_lshlrev_b32_e32 v242, 16, v52
	v_and_b32_e32 v52, 0xffff0000, v52
	v_add_f32_dpp v178, v178, v178 row_bcast:15 row_mask:0xa bank_mask:0xf
	v_lshlrev_b32_e32 v243, 16, v53
	v_and_b32_e32 v53, 0xffff0000, v53
	v_add_f32_dpp v178, v178, v178 row_bcast:31 row_mask:0xc bank_mask:0xf
	v_lshlrev_b32_e32 v244, 16, v54
	v_and_b32_e32 v54, 0xffff0000, v54
	v_lshlrev_b32_e32 v245, 16, v55
	v_and_b32_e32 v55, 0xffff0000, v55
	v_readlane_b32 s0, v178, 63
	s_nop 1
	v_mov_b32_e32 v181, s0
	v_fmamk_f32 v181, v181, 0x3a800000, v161
	v_rsq_f32_e32 v179, v181
	s_nop 0
	v_mul_f32_e32 v246, v246, v179
	v_mul_f32_e32 v40, v40, v179
	v_mul_f32_e32 v247, v247, v179
	v_mul_f32_e32 v41, v41, v179
	v_mul_f32_e32 v248, v248, v179
	v_mul_f32_e32 v42, v42, v179
	v_mul_f32_e32 v249, v249, v179
	v_mul_f32_e32 v43, v43, v179
	v_mul_f32_e32 v250, v250, v179
	v_mul_f32_e32 v44, v44, v179
	v_mul_f32_e32 v251, v251, v179
	v_mul_f32_e32 v45, v45, v179
	v_mul_f32_e32 v176, v176, v179
	v_mul_f32_e32 v46, v46, v179
	v_mul_f32_e32 v177, v177, v179
	v_mul_f32_e32 v47, v47, v179
	v_fmac_f32_e32 v238, v88, v246
	v_fmac_f32_e32 v48, v89, v40
	v_fmac_f32_e32 v239, v90, v247
	v_fmac_f32_e32 v49, v91, v41
	v_fmac_f32_e32 v240, v92, v248
	v_fmac_f32_e32 v50, v93, v42
	v_fmac_f32_e32 v241, v94, v249
	v_fmac_f32_e32 v51, v95, v43
	v_fmac_f32_e32 v242, v96, v250
	v_fmac_f32_e32 v52, v97, v44
	v_fmac_f32_e32 v243, v98, v251
	v_fmac_f32_e32 v53, v99, v45
	v_fmac_f32_e32 v244, v100, v176
	v_fmac_f32_e32 v54, v101, v46
	v_fmac_f32_e32 v245, v102, v177
	v_fmac_f32_e32 v55, v103, v47
	v_cvt_pk_bf16_f32 v120, v238, v48
	v_cvt_pk_bf16_f32 v121, v239, v49
	global_store_dwordx2 v2, v[120:121], s[4:5] offset:0 nt
	v_cvt_pk_bf16_f32 v122, v240, v50
	v_cvt_pk_bf16_f32 v123, v241, v51
	global_store_dwordx2 v2, v[122:123], s[4:5] offset:512 nt
	v_cvt_pk_bf16_f32 v124, v242, v52
	v_cvt_pk_bf16_f32 v125, v243, v53
	global_store_dwordx2 v2, v[124:125], s[4:5] offset:1024 nt
	v_cvt_pk_bf16_f32 v126, v244, v54
	v_cvt_pk_bf16_f32 v127, v245, v55
	global_store_dwordx2 v2, v[126:127], s[4:5] offset:1536 nt
	v_mul_f32_e32 v178, v238, v238
	v_fmac_f32_e32 v178, v48, v48
	v_fmac_f32_e32 v178, v239, v239
	v_fmac_f32_e32 v178, v49, v49
	v_fmac_f32_e32 v178, v240, v240
	v_fmac_f32_e32 v178, v50, v50
	v_fmac_f32_e32 v178, v241, v241
	v_fmac_f32_e32 v178, v51, v51
	v_fmac_f32_e32 v178, v242, v242
	v_fmac_f32_e32 v178, v52, v52
	v_fmac_f32_e32 v178, v243, v243
	v_fmac_f32_e32 v178, v53, v53
	v_fmac_f32_e32 v178, v244, v244
	v_fmac_f32_e32 v178, v54, v54
	v_fmac_f32_e32 v178, v245, v245
	v_fmac_f32_e32 v178, v55, v55
	s_nop 1
	v_add_f32_dpp v178, v178, v178 quad_perm:[1,0,3,2] row_mask:0xf bank_mask:0xf bound_ctrl:1
	s_nop 1
	v_add_f32_dpp v178, v178, v178 quad_perm:[2,3,0,1] row_mask:0xf bank_mask:0xf bound_ctrl:1
	s_nop 1
	v_add_f32_dpp v178, v178, v178 row_half_mirror row_mask:0xf bank_mask:0xf bound_ctrl:1
	s_nop 1
	v_add_f32_dpp v178, v178, v178 row_mirror row_mask:0xf bank_mask:0xf bound_ctrl:1
	s_nop 1
	v_add_f32_dpp v178, v178, v178 row_bcast:15 row_mask:0xa bank_mask:0xf
	s_nop 1
	v_add_f32_dpp v178, v178, v178 row_bcast:31 row_mask:0xc bank_mask:0xf
	s_nop 0
	v_readlane_b32 s0, v178, 63
	s_nop 1
	v_mov_b32_e32 v181, s0
	v_fmamk_f32 v181, v181, 0x3a800000, v161
	v_rsq_f32_e32 v180, v181
	s_nop 0
	v_mul_f32_e32 v238, v238, v180
	v_mul_f32_e32 v48, v48, v180
	v_mul_f32_e32 v239, v239, v180
	v_mul_f32_e32 v49, v49, v180
	v_mul_f32_e32 v240, v240, v180
	v_mul_f32_e32 v50, v50, v180
	v_mul_f32_e32 v241, v241, v180
	v_mul_f32_e32 v51, v51, v180
	v_mul_f32_e32 v242, v242, v180
	v_mul_f32_e32 v52, v52, v180
	v_mul_f32_e32 v243, v243, v180
	v_mul_f32_e32 v53, v53, v180
	v_mul_f32_e32 v244, v244, v180
	v_mul_f32_e32 v54, v54, v180
	v_mul_f32_e32 v245, v245, v180
	v_mul_f32_e32 v55, v55, v180
	v_fma_f32 v238, v238, v104, v134
	v_fma_f32 v48, v48, v105, v135
	v_fma_f32 v239, v239, v106, v136
	v_fma_f32 v49, v49, v107, v137
	v_fma_f32 v240, v240, v108, v138
	v_fma_f32 v50, v50, v109, v139
	v_fma_f32 v241, v241, v110, v140
	v_fma_f32 v51, v51, v111, v141
	v_fma_f32 v242, v242, v112, v142
	v_fma_f32 v52, v52, v113, v143
	v_fma_f32 v243, v243, v114, v144
	v_fma_f32 v53, v53, v115, v145
	v_fma_f32 v244, v244, v116, v146
	v_fma_f32 v54, v54, v117, v147
	v_fma_f32 v245, v245, v118, v148
	v_fma_f32 v55, v55, v119, v149
	v_cvt_pk_bf16_f32 v150, v238, v48
	v_cvt_pk_bf16_f32 v151, v239, v49
	global_store_dwordx2 v2, v[150:151], s[8:9] offset:0
	v_cvt_pk_bf16_f32 v152, v240, v50
	v_cvt_pk_bf16_f32 v153, v241, v51
	global_store_dwordx2 v2, v[152:153], s[8:9] offset:512
	v_cvt_pk_bf16_f32 v154, v242, v52
	v_cvt_pk_bf16_f32 v155, v243, v53
	global_store_dwordx2 v2, v[154:155], s[8:9] offset:1024
	v_cvt_pk_bf16_f32 v156, v244, v54
	v_cvt_pk_bf16_f32 v157, v245, v55
	global_store_dwordx2 v2, v[156:157], s[8:9] offset:1536
	s_waitcnt vmcnt(28)
	v_lshlrev_b32_e32 v246, 16, v8
	v_and_b32_e32 v8, 0xffff0000, v8
	v_lshlrev_b32_e32 v247, 16, v9
	v_and_b32_e32 v9, 0xffff0000, v9
	v_lshlrev_b32_e32 v248, 16, v10
	v_and_b32_e32 v10, 0xffff0000, v10
	v_lshlrev_b32_e32 v249, 16, v11
	v_and_b32_e32 v11, 0xffff0000, v11
	v_lshlrev_b32_e32 v250, 16, v12
	v_and_b32_e32 v12, 0xffff0000, v12
	v_lshlrev_b32_e32 v251, 16, v13
	v_and_b32_e32 v13, 0xffff0000, v13
	v_lshlrev_b32_e32 v176, 16, v14
	v_and_b32_e32 v14, 0xffff0000, v14
	v_lshlrev_b32_e32 v177, 16, v15
	v_and_b32_e32 v15, 0xffff0000, v15
	v_mul_f32_e32 v178, v246, v246
	v_fmac_f32_e32 v178, v8, v8
	v_fmac_f32_e32 v178, v247, v247
	v_fmac_f32_e32 v178, v9, v9
	v_fmac_f32_e32 v178, v248, v248
	v_fmac_f32_e32 v178, v10, v10
	v_fmac_f32_e32 v178, v249, v249
	v_fmac_f32_e32 v178, v11, v11
	v_fmac_f32_e32 v178, v250, v250
	v_fmac_f32_e32 v178, v12, v12
	v_fmac_f32_e32 v178, v251, v251
	v_fmac_f32_e32 v178, v13, v13
	v_fmac_f32_e32 v178, v176, v176
	v_fmac_f32_e32 v178, v14, v14
	v_fmac_f32_e32 v178, v177, v177
	v_fmac_f32_e32 v178, v15, v15
	s_waitcnt vmcnt(24)
	v_lshlrev_b32_e32 v238, 16, v16
	v_and_b32_e32 v16, 0xffff0000, v16
	v_add_f32_dpp v178, v178, v178 quad_perm:[1,0,3,2] row_mask:0xf bank_mask:0xf bound_ctrl:1
	v_lshlrev_b32_e32 v239, 16, v17
	v_and_b32_e32 v17, 0xffff0000, v17
	v_add_f32_dpp v178, v178, v178 quad_perm:[2,3,0,1] row_mask:0xf bank_mask:0xf bound_ctrl:1
	v_lshlrev_b32_e32 v240, 16, v18
	v_and_b32_e32 v18, 0xffff0000, v18
	v_add_f32_dpp v178, v178, v178 row_half_mirror row_mask:0xf bank_mask:0xf bound_ctrl:1
	v_lshlrev_b32_e32 v241, 16, v19
	v_and_b32_e32 v19, 0xffff0000, v19
	v_add_f32_dpp v178, v178, v178 row_mirror row_mask:0xf bank_mask:0xf bound_ctrl:1
	v_lshlrev_b32_e32 v242, 16, v20
	v_and_b32_e32 v20, 0xffff0000, v20
	v_add_f32_dpp v178, v178, v178 row_bcast:15 row_mask:0xa bank_mask:0xf
	v_lshlrev_b32_e32 v243, 16, v21
	v_and_b32_e32 v21, 0xffff0000, v21
	v_add_f32_dpp v178, v178, v178 row_bcast:31 row_mask:0xc bank_mask:0xf
	v_lshlrev_b32_e32 v244, 16, v22
	v_and_b32_e32 v22, 0xffff0000, v22
	v_lshlrev_b32_e32 v245, 16, v23
	v_and_b32_e32 v23, 0xffff0000, v23
	v_readlane_b32 s0, v178, 63
	s_nop 1
	v_mov_b32_e32 v181, s0
	v_fmamk_f32 v181, v181, 0x3a800000, v161
	v_rsq_f32_e32 v179, v181
	s_nop 0
	v_mul_f32_e32 v246, v246, v179
	v_mul_f32_e32 v8, v8, v179
	v_mul_f32_e32 v247, v247, v179
	v_mul_f32_e32 v9, v9, v179
	v_mul_f32_e32 v248, v248, v179
	v_mul_f32_e32 v10, v10, v179
	v_mul_f32_e32 v249, v249, v179
	v_mul_f32_e32 v11, v11, v179
	v_mul_f32_e32 v250, v250, v179
	v_mul_f32_e32 v12, v12, v179
	v_mul_f32_e32 v251, v251, v179
	v_mul_f32_e32 v13, v13, v179
	v_mul_f32_e32 v176, v176, v179
	v_mul_f32_e32 v14, v14, v179
	v_mul_f32_e32 v177, v177, v179
	v_mul_f32_e32 v15, v15, v179
	v_fmac_f32_e32 v238, v88, v246
	v_fmac_f32_e32 v16, v89, v8
	v_fmac_f32_e32 v239, v90, v247
	v_fmac_f32_e32 v17, v91, v9
	v_fmac_f32_e32 v240, v92, v248
	v_fmac_f32_e32 v18, v93, v10
	v_fmac_f32_e32 v241, v94, v249
	v_fmac_f32_e32 v19, v95, v11
	v_fmac_f32_e32 v242, v96, v250
	v_fmac_f32_e32 v20, v97, v12
	v_fmac_f32_e32 v243, v98, v251
	v_fmac_f32_e32 v21, v99, v13
	v_fmac_f32_e32 v244, v100, v176
	v_fmac_f32_e32 v22, v101, v14
	v_fmac_f32_e32 v245, v102, v177
	v_fmac_f32_e32 v23, v103, v15
	v_cvt_pk_bf16_f32 v120, v238, v16
	v_cvt_pk_bf16_f32 v121, v239, v17
	global_store_dwordx2 v3, v[120:121], s[4:5] offset:0 nt
	v_cvt_pk_bf16_f32 v122, v240, v18
	v_cvt_pk_bf16_f32 v123, v241, v19
	global_store_dwordx2 v3, v[122:123], s[4:5] offset:512 nt
	v_cvt_pk_bf16_f32 v124, v242, v20
	v_cvt_pk_bf16_f32 v125, v243, v21
	global_store_dwordx2 v3, v[124:125], s[4:5] offset:1024 nt
	v_cvt_pk_bf16_f32 v126, v244, v22
	v_cvt_pk_bf16_f32 v127, v245, v23
	global_store_dwordx2 v3, v[126:127], s[4:5] offset:1536 nt
	v_mul_f32_e32 v178, v238, v238
	v_fmac_f32_e32 v178, v16, v16
	v_fmac_f32_e32 v178, v239, v239
	v_fmac_f32_e32 v178, v17, v17
	v_fmac_f32_e32 v178, v240, v240
	v_fmac_f32_e32 v178, v18, v18
	v_fmac_f32_e32 v178, v241, v241
	v_fmac_f32_e32 v178, v19, v19
	v_fmac_f32_e32 v178, v242, v242
	v_fmac_f32_e32 v178, v20, v20
	v_fmac_f32_e32 v178, v243, v243
	v_fmac_f32_e32 v178, v21, v21
	v_fmac_f32_e32 v178, v244, v244
	v_fmac_f32_e32 v178, v22, v22
	v_fmac_f32_e32 v178, v245, v245
	v_fmac_f32_e32 v178, v23, v23
	s_nop 1
	v_add_f32_dpp v178, v178, v178 quad_perm:[1,0,3,2] row_mask:0xf bank_mask:0xf bound_ctrl:1
	s_nop 1
	v_add_f32_dpp v178, v178, v178 quad_perm:[2,3,0,1] row_mask:0xf bank_mask:0xf bound_ctrl:1
	s_nop 1
	v_add_f32_dpp v178, v178, v178 row_half_mirror row_mask:0xf bank_mask:0xf bound_ctrl:1
	s_nop 1
	v_add_f32_dpp v178, v178, v178 row_mirror row_mask:0xf bank_mask:0xf bound_ctrl:1
	s_nop 1
	v_add_f32_dpp v178, v178, v178 row_bcast:15 row_mask:0xa bank_mask:0xf
	s_nop 1
	v_add_f32_dpp v178, v178, v178 row_bcast:31 row_mask:0xc bank_mask:0xf
	s_nop 0
	v_readlane_b32 s0, v178, 63
	s_nop 1
	v_mov_b32_e32 v181, s0
	v_fmamk_f32 v181, v181, 0x3a800000, v161
	v_rsq_f32_e32 v180, v181
	s_nop 0
	v_mul_f32_e32 v238, v238, v180
	v_mul_f32_e32 v16, v16, v180
	v_mul_f32_e32 v239, v239, v180
	v_mul_f32_e32 v17, v17, v180
	v_mul_f32_e32 v240, v240, v180
	v_mul_f32_e32 v18, v18, v180
	v_mul_f32_e32 v241, v241, v180
	v_mul_f32_e32 v19, v19, v180
	v_mul_f32_e32 v242, v242, v180
	v_mul_f32_e32 v20, v20, v180
	v_mul_f32_e32 v243, v243, v180
	v_mul_f32_e32 v21, v21, v180
	v_mul_f32_e32 v244, v244, v180
	v_mul_f32_e32 v22, v22, v180
	v_mul_f32_e32 v245, v245, v180
	v_mul_f32_e32 v23, v23, v180
	v_fma_f32 v238, v238, v104, v134
	v_fma_f32 v16, v16, v105, v135
	v_fma_f32 v239, v239, v106, v136
	v_fma_f32 v17, v17, v107, v137
	v_fma_f32 v240, v240, v108, v138
	v_fma_f32 v18, v18, v109, v139
	v_fma_f32 v241, v241, v110, v140
	v_fma_f32 v19, v19, v111, v141
	v_fma_f32 v242, v242, v112, v142
	v_fma_f32 v20, v20, v113, v143
	v_fma_f32 v243, v243, v114, v144
	v_fma_f32 v21, v21, v115, v145
	v_fma_f32 v244, v244, v116, v146
	v_fma_f32 v22, v22, v117, v147
	v_fma_f32 v245, v245, v118, v148
	v_fma_f32 v23, v23, v119, v149
	v_cvt_pk_bf16_f32 v150, v238, v16
	v_cvt_pk_bf16_f32 v151, v239, v17
	global_store_dwordx2 v3, v[150:151], s[8:9] offset:0
	v_cvt_pk_bf16_f32 v152, v240, v18
	v_cvt_pk_bf16_f32 v153, v241, v19
	global_store_dwordx2 v3, v[152:153], s[8:9] offset:512
	v_cvt_pk_bf16_f32 v154, v242, v20
	v_cvt_pk_bf16_f32 v155, v243, v21
	global_store_dwordx2 v3, v[154:155], s[8:9] offset:1024
	v_cvt_pk_bf16_f32 v156, v244, v22
	v_cvt_pk_bf16_f32 v157, v245, v23
	global_store_dwordx2 v3, v[156:157], s[8:9] offset:1536
	s_waitcnt vmcnt(28)
	v_lshlrev_b32_e32 v246, 16, v190
	v_and_b32_e32 v190, 0xffff0000, v190
	v_lshlrev_b32_e32 v247, 16, v191
	v_and_b32_e32 v191, 0xffff0000, v191
	v_lshlrev_b32_e32 v248, 16, v192
	v_and_b32_e32 v192, 0xffff0000, v192
	v_lshlrev_b32_e32 v249, 16, v193
	v_and_b32_e32 v193, 0xffff0000, v193
	v_lshlrev_b32_e32 v250, 16, v194
	v_and_b32_e32 v194, 0xffff0000, v194
	v_lshlrev_b32_e32 v251, 16, v195
	v_and_b32_e32 v195, 0xffff0000, v195
	v_lshlrev_b32_e32 v176, 16, v196
	v_and_b32_e32 v196, 0xffff0000, v196
	v_lshlrev_b32_e32 v177, 16, v197
	v_and_b32_e32 v197, 0xffff0000, v197
	v_mul_f32_e32 v178, v246, v246
	v_fmac_f32_e32 v178, v190, v190
	v_fmac_f32_e32 v178, v247, v247
	v_fmac_f32_e32 v178, v191, v191
	v_fmac_f32_e32 v178, v248, v248
	v_fmac_f32_e32 v178, v192, v192
	v_fmac_f32_e32 v178, v249, v249
	v_fmac_f32_e32 v178, v193, v193
	v_fmac_f32_e32 v178, v250, v250
	v_fmac_f32_e32 v178, v194, v194
	v_fmac_f32_e32 v178, v251, v251
	v_fmac_f32_e32 v178, v195, v195
	v_fmac_f32_e32 v178, v176, v176
	v_fmac_f32_e32 v178, v196, v196
	v_fmac_f32_e32 v178, v177, v177
	v_fmac_f32_e32 v178, v197, v197
	s_waitcnt vmcnt(24)
	v_lshlrev_b32_e32 v238, 16, v198
	v_and_b32_e32 v198, 0xffff0000, v198
	v_add_f32_dpp v178, v178, v178 quad_perm:[1,0,3,2] row_mask:0xf bank_mask:0xf bound_ctrl:1
	v_lshlrev_b32_e32 v239, 16, v199
	v_and_b32_e32 v199, 0xffff0000, v199
	v_add_f32_dpp v178, v178, v178 quad_perm:[2,3,0,1] row_mask:0xf bank_mask:0xf bound_ctrl:1
	v_lshlrev_b32_e32 v240, 16, v200
	v_and_b32_e32 v200, 0xffff0000, v200
	v_add_f32_dpp v178, v178, v178 row_half_mirror row_mask:0xf bank_mask:0xf bound_ctrl:1
	v_lshlrev_b32_e32 v241, 16, v201
	v_and_b32_e32 v201, 0xffff0000, v201
	v_add_f32_dpp v178, v178, v178 row_mirror row_mask:0xf bank_mask:0xf bound_ctrl:1
	v_lshlrev_b32_e32 v242, 16, v202
	v_and_b32_e32 v202, 0xffff0000, v202
	v_add_f32_dpp v178, v178, v178 row_bcast:15 row_mask:0xa bank_mask:0xf
	v_lshlrev_b32_e32 v243, 16, v203
	v_and_b32_e32 v203, 0xffff0000, v203
	v_add_f32_dpp v178, v178, v178 row_bcast:31 row_mask:0xc bank_mask:0xf
	v_lshlrev_b32_e32 v244, 16, v204
	v_and_b32_e32 v204, 0xffff0000, v204
	v_lshlrev_b32_e32 v245, 16, v205
	v_and_b32_e32 v205, 0xffff0000, v205
	v_readlane_b32 s0, v178, 63
	s_nop 1
	v_mov_b32_e32 v181, s0
	v_fmamk_f32 v181, v181, 0x3a800000, v161
	v_rsq_f32_e32 v179, v181
	s_nop 0
	v_mul_f32_e32 v246, v246, v179
	v_mul_f32_e32 v190, v190, v179
	v_mul_f32_e32 v247, v247, v179
	v_mul_f32_e32 v191, v191, v179
	v_mul_f32_e32 v248, v248, v179
	v_mul_f32_e32 v192, v192, v179
	v_mul_f32_e32 v249, v249, v179
	v_mul_f32_e32 v193, v193, v179
	v_mul_f32_e32 v250, v250, v179
	v_mul_f32_e32 v194, v194, v179
	v_mul_f32_e32 v251, v251, v179
	v_mul_f32_e32 v195, v195, v179
	v_mul_f32_e32 v176, v176, v179
	v_mul_f32_e32 v196, v196, v179
	v_mul_f32_e32 v177, v177, v179
	v_mul_f32_e32 v197, v197, v179
	v_fmac_f32_e32 v238, v88, v246
	v_fmac_f32_e32 v198, v89, v190
	v_fmac_f32_e32 v239, v90, v247
	v_fmac_f32_e32 v199, v91, v191
	v_fmac_f32_e32 v240, v92, v248
	v_fmac_f32_e32 v200, v93, v192
	v_fmac_f32_e32 v241, v94, v249
	v_fmac_f32_e32 v201, v95, v193
	v_fmac_f32_e32 v242, v96, v250
	v_fmac_f32_e32 v202, v97, v194
	v_fmac_f32_e32 v243, v98, v251
	v_fmac_f32_e32 v203, v99, v195
	v_fmac_f32_e32 v244, v100, v176
	v_fmac_f32_e32 v204, v101, v196
	v_fmac_f32_e32 v245, v102, v177
	v_fmac_f32_e32 v205, v103, v197
	v_cvt_pk_bf16_f32 v120, v238, v198
	v_cvt_pk_bf16_f32 v121, v239, v199
	global_store_dwordx2 v4, v[120:121], s[4:5] offset:0 nt
	v_cvt_pk_bf16_f32 v122, v240, v200
	v_cvt_pk_bf16_f32 v123, v241, v201
	global_store_dwordx2 v4, v[122:123], s[4:5] offset:512 nt
	v_cvt_pk_bf16_f32 v124, v242, v202
	v_cvt_pk_bf16_f32 v125, v243, v203
	global_store_dwordx2 v4, v[124:125], s[4:5] offset:1024 nt
	v_cvt_pk_bf16_f32 v126, v244, v204
	v_cvt_pk_bf16_f32 v127, v245, v205
	global_store_dwordx2 v4, v[126:127], s[4:5] offset:1536 nt
	v_mul_f32_e32 v178, v238, v238
	v_fmac_f32_e32 v178, v198, v198
	v_fmac_f32_e32 v178, v239, v239
	v_fmac_f32_e32 v178, v199, v199
	v_fmac_f32_e32 v178, v240, v240
	v_fmac_f32_e32 v178, v200, v200
	v_fmac_f32_e32 v178, v241, v241
	v_fmac_f32_e32 v178, v201, v201
	v_fmac_f32_e32 v178, v242, v242
	v_fmac_f32_e32 v178, v202, v202
	v_fmac_f32_e32 v178, v243, v243
	v_fmac_f32_e32 v178, v203, v203
	v_fmac_f32_e32 v178, v244, v244
	v_fmac_f32_e32 v178, v204, v204
	v_fmac_f32_e32 v178, v245, v245
	v_fmac_f32_e32 v178, v205, v205
	s_nop 1
	v_add_f32_dpp v178, v178, v178 quad_perm:[1,0,3,2] row_mask:0xf bank_mask:0xf bound_ctrl:1
	s_nop 1
	v_add_f32_dpp v178, v178, v178 quad_perm:[2,3,0,1] row_mask:0xf bank_mask:0xf bound_ctrl:1
	s_nop 1
	v_add_f32_dpp v178, v178, v178 row_half_mirror row_mask:0xf bank_mask:0xf bound_ctrl:1
	s_nop 1
	v_add_f32_dpp v178, v178, v178 row_mirror row_mask:0xf bank_mask:0xf bound_ctrl:1
	s_nop 1
	v_add_f32_dpp v178, v178, v178 row_bcast:15 row_mask:0xa bank_mask:0xf
	s_nop 1
	v_add_f32_dpp v178, v178, v178 row_bcast:31 row_mask:0xc bank_mask:0xf
	s_nop 0
	v_readlane_b32 s0, v178, 63
	s_nop 1
	v_mov_b32_e32 v181, s0
	v_fmamk_f32 v181, v181, 0x3a800000, v161
	v_rsq_f32_e32 v180, v181
	s_nop 0
	v_mul_f32_e32 v238, v238, v180
	v_mul_f32_e32 v198, v198, v180
	v_mul_f32_e32 v239, v239, v180
	v_mul_f32_e32 v199, v199, v180
	v_mul_f32_e32 v240, v240, v180
	v_mul_f32_e32 v200, v200, v180
	v_mul_f32_e32 v241, v241, v180
	v_mul_f32_e32 v201, v201, v180
	v_mul_f32_e32 v242, v242, v180
	v_mul_f32_e32 v202, v202, v180
	v_mul_f32_e32 v243, v243, v180
	v_mul_f32_e32 v203, v203, v180
	v_mul_f32_e32 v244, v244, v180
	v_mul_f32_e32 v204, v204, v180
	v_mul_f32_e32 v245, v245, v180
	v_mul_f32_e32 v205, v205, v180
	v_fma_f32 v238, v238, v104, v134
	v_fma_f32 v198, v198, v105, v135
	v_fma_f32 v239, v239, v106, v136
	v_fma_f32 v199, v199, v107, v137
	v_fma_f32 v240, v240, v108, v138
	v_fma_f32 v200, v200, v109, v139
	v_fma_f32 v241, v241, v110, v140
	v_fma_f32 v201, v201, v111, v141
	v_fma_f32 v242, v242, v112, v142
	v_fma_f32 v202, v202, v113, v143
	v_fma_f32 v243, v243, v114, v144
	v_fma_f32 v203, v203, v115, v145
	v_fma_f32 v244, v244, v116, v146
	v_fma_f32 v204, v204, v117, v147
	v_fma_f32 v245, v245, v118, v148
	v_fma_f32 v205, v205, v119, v149
	v_cvt_pk_bf16_f32 v150, v238, v198
	v_cvt_pk_bf16_f32 v151, v239, v199
	global_store_dwordx2 v4, v[150:151], s[8:9] offset:0
	v_cvt_pk_bf16_f32 v152, v240, v200
	v_cvt_pk_bf16_f32 v153, v241, v201
	global_store_dwordx2 v4, v[152:153], s[8:9] offset:512
	v_cvt_pk_bf16_f32 v154, v242, v202
	v_cvt_pk_bf16_f32 v155, v243, v203
	global_store_dwordx2 v4, v[154:155], s[8:9] offset:1024
	v_cvt_pk_bf16_f32 v156, v244, v204
	v_cvt_pk_bf16_f32 v157, v245, v205
	global_store_dwordx2 v4, v[156:157], s[8:9] offset:1536
	s_branch .LBB0_100
.Lrow2_last:
	v_readfirstlane_b32 s0, v160
	v_readlane_b32 s1, v252, 7
	s_lshr_b32 s0, s0, 6
	s_mov_b32 s73, s0
	s_add_i32 s0, s0, s1
	v_readlane_b32 s62, v254, 34
	s_sub_u32 s64, s78, 0x110
	s_subb_u32 s65, s79, 0
	s_load_dwordx2 s[66:67], s[64:65], 0x40
	s_load_dwordx2 s[10:11], s[64:65], 0xf8
	s_lshl_b32 s63, s0, 11
	s_add_u32 s4, s84, 0x167ca000
	s_addc_u32 s5, s85, 0
	s_add_u32 s4, s4, s63
	s_addc_u32 s5, s5, 0
	s_add_u32 s6, s84, 0x112ca000
	s_addc_u32 s7, s85, 0
	s_add_u32 s6, s6, s63
	s_addc_u32 s7, s7, 0
	v_and_b32_e32 v0, 63, v160
	v_lshlrev_b32_e32 v1, 4, v0
	v_lshlrev_b32_e32 v0, 3, v0
	v_add_u32_e32 v2, 0x400000, v0
	v_add_u32_e32 v3, 0x800000, v0
	v_add_u32_e32 v4, 0xc00000, v0
	v_add_u32_e32 v5, 0x1000000, v0
	global_load_dwordx2 v[8:9], v5, s[6:7] offset:0 nt
	global_load_dwordx2 v[10:11], v5, s[6:7] offset:512 nt
	global_load_dwordx2 v[12:13], v5, s[6:7] offset:1024 nt
	global_load_dwordx2 v[14:15], v5, s[6:7] offset:1536 nt
	global_load_dwordx2 v[16:17], v5, s[4:5] offset:0 nt
	global_load_dwordx2 v[18:19], v5, s[4:5] offset:512 nt
	global_load_dwordx2 v[20:21], v5, s[4:5] offset:1024 nt
	global_load_dwordx2 v[22:23], v5, s[4:5] offset:1536 nt
	s_add_u32 s8, s84, 0xaeca000
	s_addc_u32 s9, s85, 0
	s_add_u32 s8, s8, s63
	s_addc_u32 s9, s9, 0
	s_lshr_b32 s69, s0, 10
	s_add_i32 s69, s69, 1
	s_mul_i32 s69, s69, 0x6000
	s_mul_i32 s68, s62, 0x12000
	s_mov_b32 s70, 0
	s_mul_i32 s71, s70, 0x12000
	s_lshl_b32 s70, s70, 14
	s_lshl_b32 s72, s62, 14
	s_add_i32 s72, s72, 0x3000
	s_add_u32 s16, s84, 0x6605000
	s_addc_u32 s17, s85, 0
	s_add_u32 s16, s16, s68
	s_addc_u32 s17, s17, 0
	s_add_u32 s20, s84, 0x6600000
	s_addc_u32 s21, s85, 0
	s_add_u32 s20, s20, s71
	s_addc_u32 s21, s21, 0
	s_add_u32 s18, s20, 0x1000
	s_addc_u32 s19, s21, 0
	s_add_u32 s22, s16, s69
	s_addc_u32 s23, s17, 0
	s_add_u32 s60, s20, s69
	s_addc_u32 s61, s21, 0
	s_add_u32 s26, s18, s69
	s_addc_u32 s27, s19, 0
	s_lshl_b32 s63, s63, 1
	s_waitcnt lgkmcnt(0)
	s_add_u32 s12, s66, s72
	s_addc_u32 s13, s67, 0
	s_add_u32 s14, s66, s70
	s_addc_u32 s15, s67, 0
	s_add_u32 s10, s10, s63
	s_addc_u32 s11, s11, 0
	s_mov_b64 s[74:75], s[12:13]
	s_cmp_eq_u32 s73, 1
	s_cselect_b32 s74, s14, s74
	s_cselect_b32 s75, s15, s75
	s_cmp_eq_u32 s73, 2
	s_cselect_b32 s74, s16, s74
	s_cselect_b32 s75, s17, s75
	s_cmp_eq_u32 s73, 3
	s_cselect_b32 s74, s18, s74
	s_cselect_b32 s75, s19, s75
	s_cmp_eq_u32 s73, 4
	s_cselect_b32 s74, s20, s74
	s_cselect_b32 s75, s21, s75
	s_cmp_eq_u32 s73, 5
	s_cselect_b32 s74, s22, s74
	s_cselect_b32 s75, s23, s75
	s_cmp_eq_u32 s73, 6
	s_cselect_b32 s74, s26, s74
	s_cselect_b32 s75, s27, s75
	s_cmp_eq_u32 s73, 7
	s_cselect_b32 s74, s60, s74
	s_cselect_b32 s75, s61, s75
	global_load_dwordx4 v[222:225], v1, s[74:75] offset:0
	global_load_dwordx4 v[226:229], v1, s[74:75] offset:1024
	global_load_dwordx4 v[230:233], v1, s[74:75] offset:2048
	global_load_dwordx4 v[234:237], v1, s[74:75] offset:3072
	s_lshl_b32 s74, s73, 12
	v_add_u32_e32 v6, s74, v1
	global_load_dwordx2 v[24:25], v0, s[6:7] offset:0 nt
	global_load_dwordx2 v[26:27], v0, s[6:7] offset:512 nt
	global_load_dwordx2 v[28:29], v0, s[6:7] offset:1024 nt
	global_load_dwordx2 v[30:31], v0, s[6:7] offset:1536 nt
	global_load_dwordx2 v[32:33], v0, s[4:5] offset:0 nt
	global_load_dwordx2 v[34:35], v0, s[4:5] offset:512 nt
	global_load_dwordx2 v[36:37], v0, s[4:5] offset:1024 nt
	global_load_dwordx2 v[38:39], v0, s[4:5] offset:1536 nt
	global_load_dwordx2 v[40:41], v2, s[6:7] offset:0 nt
	global_load_dwordx2 v[42:43], v2, s[6:7] offset:512 nt
	global_load_dwordx2 v[44:45], v2, s[6:7] offset:1024 nt
	global_load_dwordx2 v[46:47], v2, s[6:7] offset:1536 nt
	global_load_dwordx2 v[48:49], v2, s[4:5] offset:0 nt
	global_load_dwordx2 v[50:51], v2, s[4:5] offset:512 nt
	global_load_dwordx2 v[52:53], v2, s[4:5] offset:1024 nt
	global_load_dwordx2 v[54:55], v2, s[4:5] offset:1536 nt
	s_waitcnt vmcnt(16)
	ds_write_b128 v6, v[222:225] offset:0
	ds_write_b128 v6, v[226:229] offset:1024
	ds_write_b128 v6, v[230:233] offset:2048
	ds_write_b128 v6, v[234:237] offset:3072
	s_waitcnt lgkmcnt(0)
	s_barrier
	ds_read_b128 v[56:59], v1 offset:0
	ds_read_b128 v[60:63], v1 offset:1024
	ds_read_b128 v[64:67], v1 offset:2048
	ds_read_b128 v[68:71], v1 offset:3072
	ds_read_b128 v[88:91], v1 offset:8192
	ds_read_b128 v[92:95], v1 offset:9216
	ds_read_b128 v[96:99], v1 offset:10240
	ds_read_b128 v[100:103], v1 offset:11264
	ds_read_b128 v[190:193], v1 offset:20480
	ds_read_b128 v[194:197], v1 offset:21504
	ds_read_b128 v[198:201], v1 offset:22528
	ds_read_b128 v[202:205], v1 offset:23552
	v_lshlrev_b32_e32 v246, 16, v8
	v_and_b32_e32 v8, 0xffff0000, v8
	v_lshlrev_b32_e32 v247, 16, v9
	v_and_b32_e32 v9, 0xffff0000, v9
	v_lshlrev_b32_e32 v248, 16, v10
	v_and_b32_e32 v10, 0xffff0000, v10
	v_lshlrev_b32_e32 v249, 16, v11
	v_and_b32_e32 v11, 0xffff0000, v11
	v_lshlrev_b32_e32 v250, 16, v12
	v_and_b32_e32 v12, 0xffff0000, v12
	v_lshlrev_b32_e32 v251, 16, v13
	v_and_b32_e32 v13, 0xffff0000, v13
	v_lshlrev_b32_e32 v176, 16, v14
	v_and_b32_e32 v14, 0xffff0000, v14
	v_lshlrev_b32_e32 v177, 16, v15
	v_and_b32_e32 v15, 0xffff0000, v15
	v_mul_f32_e32 v178, v246, v246
	v_fmac_f32_e32 v178, v8, v8
	v_fmac_f32_e32 v178, v247, v247
	v_fmac_f32_e32 v178, v9, v9
	v_fmac_f32_e32 v178, v248, v248
	v_fmac_f32_e32 v178, v10, v10
	v_fmac_f32_e32 v178, v249, v249
	v_fmac_f32_e32 v178, v11, v11
	v_fmac_f32_e32 v178, v250, v250
	v_fmac_f32_e32 v178, v12, v12
	v_fmac_f32_e32 v178, v251, v251
	v_fmac_f32_e32 v178, v13, v13
	v_fmac_f32_e32 v178, v176, v176
	v_fmac_f32_e32 v178, v14, v14
	v_fmac_f32_e32 v178, v177, v177
	v_fmac_f32_e32 v178, v15, v15
	v_lshlrev_b32_e32 v238, 16, v16
	v_and_b32_e32 v16, 0xffff0000, v16
	v_add_f32_dpp v178, v178, v178 quad_perm:[1,0,3,2] row_mask:0xf bank_mask:0xf bound_ctrl:1
	v_lshlrev_b32_e32 v239, 16, v17
	v_and_b32_e32 v17, 0xffff0000, v17
	v_add_f32_dpp v178, v178, v178 quad_perm:[2,3,0,1] row_mask:0xf bank_mask:0xf bound_ctrl:1
	v_lshlrev_b32_e32 v240, 16, v18
	v_and_b32_e32 v18, 0xffff0000, v18
	v_add_f32_dpp v178, v178, v178 row_half_mirror row_mask:0xf bank_mask:0xf bound_ctrl:1
	v_lshlrev_b32_e32 v241, 16, v19
	v_and_b32_e32 v19, 0xffff0000, v19
	v_add_f32_dpp v178, v178, v178 row_mirror row_mask:0xf bank_mask:0xf bound_ctrl:1
	v_lshlrev_b32_e32 v242, 16, v20
	v_and_b32_e32 v20, 0xffff0000, v20
	v_add_f32_dpp v178, v178, v178 row_bcast:15 row_mask:0xa bank_mask:0xf
	v_lshlrev_b32_e32 v243, 16, v21
	v_and_b32_e32 v21, 0xffff0000, v21
	v_add_f32_dpp v178, v178, v178 row_bcast:31 row_mask:0xc bank_mask:0xf
	v_lshlrev_b32_e32 v244, 16, v22
	v_and_b32_e32 v22, 0xffff0000, v22
	v_lshlrev_b32_e32 v245, 16, v23
	v_and_b32_e32 v23, 0xffff0000, v23
	v_readlane_b32 s0, v178, 63
	s_nop 1
	v_mov_b32_e32 v181, s0
	v_fmamk_f32 v181, v181, 0x3a800000, v161
	v_rsq_f32_e32 v179, v181
	s_nop 0
	s_waitcnt lgkmcnt(0)
	v_mul_f32_e32 v190, v190, v56
	v_mul_f32_e32 v191, v191, v57
	v_mul_f32_e32 v192, v192, v58
	v_mul_f32_e32 v193, v193, v59
	v_mul_f32_e32 v194, v194, v60
	v_mul_f32_e32 v195, v195, v61
	v_mul_f32_e32 v196, v196, v62
	v_mul_f32_e32 v197, v197, v63
	v_mul_f32_e32 v198, v198, v64
	v_mul_f32_e32 v199, v199, v65
	v_mul_f32_e32 v200, v200, v66
	v_mul_f32_e32 v201, v201, v67
	v_mul_f32_e32 v202, v202, v68
	v_mul_f32_e32 v203, v203, v69
	v_mul_f32_e32 v204, v204, v70
	v_mul_f32_e32 v205, v205, v71
	v_mul_f32_e32 v88, v88, v56
	v_mul_f32_e32 v89, v89, v57
	v_mul_f32_e32 v90, v90, v58
	v_mul_f32_e32 v91, v91, v59
	v_mul_f32_e32 v92, v92, v60
	v_mul_f32_e32 v93, v93, v61
	v_mul_f32_e32 v94, v94, v62
	v_mul_f32_e32 v95, v95, v63
	v_mul_f32_e32 v96, v96, v64
	v_mul_f32_e32 v97, v97, v65
	v_mul_f32_e32 v98, v98, v66
	v_mul_f32_e32 v99, v99, v67
	v_mul_f32_e32 v100, v100, v68
	v_mul_f32_e32 v101, v101, v69
	v_mul_f32_e32 v102, v102, v70
	v_mul_f32_e32 v103, v103, v71
	v_mul_f32_e32 v246, v246, v179
	v_mul_f32_e32 v8, v8, v179
	v_mul_f32_e32 v247, v247, v179
	v_mul_f32_e32 v9, v9, v179
	v_mul_f32_e32 v248, v248, v179
	v_mul_f32_e32 v10, v10, v179
	v_mul_f32_e32 v249, v249, v179
	v_mul_f32_e32 v11, v11, v179
	v_mul_f32_e32 v250, v250, v179
	v_mul_f32_e32 v12, v12, v179
	v_mul_f32_e32 v251, v251, v179
	v_mul_f32_e32 v13, v13, v179
	v_mul_f32_e32 v176, v176, v179
	v_mul_f32_e32 v14, v14, v179
	v_mul_f32_e32 v177, v177, v179
	v_mul_f32_e32 v15, v15, v179
	v_fmac_f32_e32 v238, v190, v246
	v_fmac_f32_e32 v16, v191, v8
	v_fmac_f32_e32 v239, v192, v247
	v_fmac_f32_e32 v17, v193, v9
	v_fmac_f32_e32 v240, v194, v248
	v_fmac_f32_e32 v18, v195, v10
	v_fmac_f32_e32 v241, v196, v249
	v_fmac_f32_e32 v19, v197, v11
	v_fmac_f32_e32 v242, v198, v250
	v_fmac_f32_e32 v20, v199, v12
	v_fmac_f32_e32 v243, v200, v251
	v_fmac_f32_e32 v21, v201, v13
	v_fmac_f32_e32 v244, v202, v176
	v_fmac_f32_e32 v22, v203, v14
	v_fmac_f32_e32 v245, v204, v177
	v_fmac_f32_e32 v23, v205, v15
	v_add_u32_e32 v181, 0x2000000, v1
	v_mov_b32_e32 v120, v238
	v_mov_b32_e32 v121, v16
	v_mov_b32_e32 v122, v239
	v_mov_b32_e32 v123, v17
	global_store_dwordx4 v181, v[120:123], s[10:11] offset:0
	v_mov_b32_e32 v124, v240
	v_mov_b32_e32 v125, v18
	v_mov_b32_e32 v126, v241
	v_mov_b32_e32 v127, v19
	global_store_dwordx4 v181, v[124:127], s[10:11] offset:1024
	v_mov_b32_e32 v150, v242
	v_mov_b32_e32 v151, v20
	v_mov_b32_e32 v152, v243
	v_mov_b32_e32 v153, v21
	global_store_dwordx4 v181, v[150:153], s[10:11] offset:2048
	v_mov_b32_e32 v154, v244
	v_mov_b32_e32 v155, v22
	v_mov_b32_e32 v156, v245
	v_mov_b32_e32 v157, v23
	global_store_dwordx4 v181, v[154:157], s[10:11] offset:3072
	global_load_dwordx2 v[8:9], v3, s[6:7] offset:0 nt
	global_load_dwordx2 v[10:11], v3, s[6:7] offset:512 nt
	global_load_dwordx2 v[12:13], v3, s[6:7] offset:1024 nt
	global_load_dwordx2 v[14:15], v3, s[6:7] offset:1536 nt
	global_load_dwordx2 v[16:17], v3, s[4:5] offset:0 nt
	global_load_dwordx2 v[18:19], v3, s[4:5] offset:512 nt
	global_load_dwordx2 v[20:21], v3, s[4:5] offset:1024 nt
	global_load_dwordx2 v[22:23], v3, s[4:5] offset:1536 nt
	global_load_dwordx2 v[190:191], v4, s[6:7] offset:0 nt
	global_load_dwordx2 v[192:193], v4, s[6:7] offset:512 nt
	global_load_dwordx2 v[194:195], v4, s[6:7] offset:1024 nt
	global_load_dwordx2 v[196:197], v4, s[6:7] offset:1536 nt
	global_load_dwordx2 v[198:199], v4, s[4:5] offset:0 nt
	global_load_dwordx2 v[200:201], v4, s[4:5] offset:512 nt
	global_load_dwordx2 v[202:203], v4, s[4:5] offset:1024 nt
	global_load_dwordx2 v[204:205], v4, s[4:5] offset:1536 nt
	s_waitcnt vmcnt(32)
	v_lshlrev_b32_e32 v246, 16, v24
	v_and_b32_e32 v24, 0xffff0000, v24
	v_lshlrev_b32_e32 v247, 16, v25
	v_and_b32_e32 v25, 0xffff0000, v25
	v_lshlrev_b32_e32 v248, 16, v26
	v_and_b32_e32 v26, 0xffff0000, v26
	v_lshlrev_b32_e32 v249, 16, v27
	v_and_b32_e32 v27, 0xffff0000, v27
	v_lshlrev_b32_e32 v250, 16, v28
	v_and_b32_e32 v28, 0xffff0000, v28
	v_lshlrev_b32_e32 v251, 16, v29
	v_and_b32_e32 v29, 0xffff0000, v29
	v_lshlrev_b32_e32 v176, 16, v30
	v_and_b32_e32 v30, 0xffff0000, v30
	v_lshlrev_b32_e32 v177, 16, v31
	v_and_b32_e32 v31, 0xffff0000, v31
	v_mul_f32_e32 v178, v246, v246
	v_fmac_f32_e32 v178, v24, v24
	v_fmac_f32_e32 v178, v247, v247
	v_fmac_f32_e32 v178, v25, v25
	v_fmac_f32_e32 v178, v248, v248
	v_fmac_f32_e32 v178, v26, v26
	v_fmac_f32_e32 v178, v249, v249
	v_fmac_f32_e32 v178, v27, v27
	v_fmac_f32_e32 v178, v250, v250
	v_fmac_f32_e32 v178, v28, v28
	v_fmac_f32_e32 v178, v251, v251
	v_fmac_f32_e32 v178, v29, v29
	v_fmac_f32_e32 v178, v176, v176
	v_fmac_f32_e32 v178, v30, v30
	v_fmac_f32_e32 v178, v177, v177
	v_fmac_f32_e32 v178, v31, v31
	s_waitcnt vmcnt(28)
	v_lshlrev_b32_e32 v238, 16, v32
	v_and_b32_e32 v32, 0xffff0000, v32
	v_add_f32_dpp v178, v178, v178 quad_perm:[1,0,3,2] row_mask:0xf bank_mask:0xf bound_ctrl:1
	v_lshlrev_b32_e32 v239, 16, v33
	v_and_b32_e32 v33, 0xffff0000, v33
	v_add_f32_dpp v178, v178, v178 quad_perm:[2,3,0,1] row_mask:0xf bank_mask:0xf bound_ctrl:1
	v_lshlrev_b32_e32 v240, 16, v34
	v_and_b32_e32 v34, 0xffff0000, v34
	v_add_f32_dpp v178, v178, v178 row_half_mirror row_mask:0xf bank_mask:0xf bound_ctrl:1
	v_lshlrev_b32_e32 v241, 16, v35
	v_and_b32_e32 v35, 0xffff0000, v35
	v_add_f32_dpp v178, v178, v178 row_mirror row_mask:0xf bank_mask:0xf bound_ctrl:1
	v_lshlrev_b32_e32 v242, 16, v36
	v_and_b32_e32 v36, 0xffff0000, v36
	v_add_f32_dpp v178, v178, v178 row_bcast:15 row_mask:0xa bank_mask:0xf
	v_lshlrev_b32_e32 v243, 16, v37
	v_and_b32_e32 v37, 0xffff0000, v37
	v_add_f32_dpp v178, v178, v178 row_bcast:31 row_mask:0xc bank_mask:0xf
	v_lshlrev_b32_e32 v244, 16, v38
	v_and_b32_e32 v38, 0xffff0000, v38
	v_lshlrev_b32_e32 v245, 16, v39
	v_and_b32_e32 v39, 0xffff0000, v39
	v_readlane_b32 s0, v178, 63
	s_nop 1
	v_mov_b32_e32 v181, s0
	v_fmamk_f32 v181, v181, 0x3a800000, v161
	v_rsq_f32_e32 v179, v181
	s_nop 0
	v_mul_f32_e32 v246, v246, v179
	v_mul_f32_e32 v24, v24, v179
	v_mul_f32_e32 v247, v247, v179
	v_mul_f32_e32 v25, v25, v179
	v_mul_f32_e32 v248, v248, v179
	v_mul_f32_e32 v26, v26, v179
	v_mul_f32_e32 v249, v249, v179
	v_mul_f32_e32 v27, v27, v179
	v_mul_f32_e32 v250, v250, v179
	v_mul_f32_e32 v28, v28, v179
	v_mul_f32_e32 v251, v251, v179
	v_mul_f32_e32 v29, v29, v179
	v_mul_f32_e32 v176, v176, v179
	v_mul_f32_e32 v30, v30, v179
	v_mul_f32_e32 v177, v177, v179
	v_mul_f32_e32 v31, v31, v179
	v_fmac_f32_e32 v238, v88, v246
	v_fmac_f32_e32 v32, v89, v24
	v_fmac_f32_e32 v239, v90, v247
	v_fmac_f32_e32 v33, v91, v25
	v_fmac_f32_e32 v240, v92, v248
	v_fmac_f32_e32 v34, v93, v26
	v_fmac_f32_e32 v241, v94, v249
	v_fmac_f32_e32 v35, v95, v27
	v_fmac_f32_e32 v242, v96, v250
	v_fmac_f32_e32 v36, v97, v28
	v_fmac_f32_e32 v243, v98, v251
	v_fmac_f32_e32 v37, v99, v29
	v_fmac_f32_e32 v244, v100, v176
	v_fmac_f32_e32 v38, v101, v30
	v_fmac_f32_e32 v245, v102, v177
	v_fmac_f32_e32 v39, v103, v31
	v_add_u32_e32 v181, 0x0, v1
	v_mov_b32_e32 v120, v238
	v_mov_b32_e32 v121, v32
	v_mov_b32_e32 v122, v239
	v_mov_b32_e32 v123, v33
	global_store_dwordx4 v181, v[120:123], s[10:11] offset:0
	v_mov_b32_e32 v124, v240
	v_mov_b32_e32 v125, v34
	v_mov_b32_e32 v126, v241
	v_mov_b32_e32 v127, v35
	global_store_dwordx4 v181, v[124:127], s[10:11] offset:1024
	v_mov_b32_e32 v150, v242
	v_mov_b32_e32 v151, v36
	v_mov_b32_e32 v152, v243
	v_mov_b32_e32 v153, v37
	global_store_dwordx4 v181, v[150:153], s[10:11] offset:2048
	v_mov_b32_e32 v154, v244
	v_mov_b32_e32 v155, v38
	v_mov_b32_e32 v156, v245
	v_mov_b32_e32 v157, v39
	global_store_dwordx4 v181, v[154:157], s[10:11] offset:3072
	s_waitcnt vmcnt(28)
	v_lshlrev_b32_e32 v246, 16, v40
	v_and_b32_e32 v40, 0xffff0000, v40
	v_lshlrev_b32_e32 v247, 16, v41
	v_and_b32_e32 v41, 0xffff0000, v41
	v_lshlrev_b32_e32 v248, 16, v42
	v_and_b32_e32 v42, 0xffff0000, v42
	v_lshlrev_b32_e32 v249, 16, v43
	v_and_b32_e32 v43, 0xffff0000, v43
	v_lshlrev_b32_e32 v250, 16, v44
	v_and_b32_e32 v44, 0xffff0000, v44
	v_lshlrev_b32_e32 v251, 16, v45
	v_and_b32_e32 v45, 0xffff0000, v45
	v_lshlrev_b32_e32 v176, 16, v46
	v_and_b32_e32 v46, 0xffff0000, v46
	v_lshlrev_b32_e32 v177, 16, v47
	v_and_b32_e32 v47, 0xffff0000, v47
	v_mul_f32_e32 v178, v246, v246
	v_fmac_f32_e32 v178, v40, v40
	v_fmac_f32_e32 v178, v247, v247
	v_fmac_f32_e32 v178, v41, v41
	v_fmac_f32_e32 v178, v248, v248
	v_fmac_f32_e32 v178, v42, v42
	v_fmac_f32_e32 v178, v249, v249
	v_fmac_f32_e32 v178, v43, v43
	v_fmac_f32_e32 v178, v250, v250
	v_fmac_f32_e32 v178, v44, v44
	v_fmac_f32_e32 v178, v251, v251
	v_fmac_f32_e32 v178, v45, v45
	v_fmac_f32_e32 v178, v176, v176
	v_fmac_f32_e32 v178, v46, v46
	v_fmac_f32_e32 v178, v177, v177
	v_fmac_f32_e32 v178, v47, v47
	s_waitcnt vmcnt(24)
	v_lshlrev_b32_e32 v238, 16, v48
	v_and_b32_e32 v48, 0xffff0000, v48
	v_add_f32_dpp v178, v178, v178 quad_perm:[1,0,3,2] row_mask:0xf bank_mask:0xf bound_ctrl:1
	v_lshlrev_b32_e32 v239, 16, v49
	v_and_b32_e32 v49, 0xffff0000, v49
	v_add_f32_dpp v178, v178, v178 quad_perm:[2,3,0,1] row_mask:0xf bank_mask:0xf bound_ctrl:1
	v_lshlrev_b32_e32 v240, 16, v50
	v_and_b32_e32 v50, 0xffff0000, v50
	v_add_f32_dpp v178, v178, v178 row_half_mirror row_mask:0xf bank_mask:0xf bound_ctrl:1
	v_lshlrev_b32_e32 v241, 16, v51
	v_and_b32_e32 v51, 0xffff0000, v51
	v_add_f32_dpp v178, v178, v178 row_mirror row_mask:0xf bank_mask:0xf bound_ctrl:1
	v_lshlrev_b32_e32 v242, 16, v52
	v_and_b32_e32 v52, 0xffff0000, v52
	v_add_f32_dpp v178, v178, v178 row_bcast:15 row_mask:0xa bank_mask:0xf
	v_lshlrev_b32_e32 v243, 16, v53
	v_and_b32_e32 v53, 0xffff0000, v53
	v_add_f32_dpp v178, v178, v178 row_bcast:31 row_mask:0xc bank_mask:0xf
	v_lshlrev_b32_e32 v244, 16, v54
	v_and_b32_e32 v54, 0xffff0000, v54
	v_lshlrev_b32_e32 v245, 16, v55
	v_and_b32_e32 v55, 0xffff0000, v55
	v_readlane_b32 s0, v178, 63
	s_nop 1
	v_mov_b32_e32 v181, s0
	v_fmamk_f32 v181, v181, 0x3a800000, v161
	v_rsq_f32_e32 v179, v181
	s_nop 0
	v_mul_f32_e32 v246, v246, v179
	v_mul_f32_e32 v40, v40, v179
	v_mul_f32_e32 v247, v247, v179
	v_mul_f32_e32 v41, v41, v179
	v_mul_f32_e32 v248, v248, v179
	v_mul_f32_e32 v42, v42, v179
	v_mul_f32_e32 v249, v249, v179
	v_mul_f32_e32 v43, v43, v179
	v_mul_f32_e32 v250, v250, v179
	v_mul_f32_e32 v44, v44, v179
	v_mul_f32_e32 v251, v251, v179
	v_mul_f32_e32 v45, v45, v179
	v_mul_f32_e32 v176, v176, v179
	v_mul_f32_e32 v46, v46, v179
	v_mul_f32_e32 v177, v177, v179
	v_mul_f32_e32 v47, v47, v179
	v_fmac_f32_e32 v238, v88, v246
	v_fmac_f32_e32 v48, v89, v40
	v_fmac_f32_e32 v239, v90, v247
	v_fmac_f32_e32 v49, v91, v41
	v_fmac_f32_e32 v240, v92, v248
	v_fmac_f32_e32 v50, v93, v42
	v_fmac_f32_e32 v241, v94, v249
	v_fmac_f32_e32 v51, v95, v43
	v_fmac_f32_e32 v242, v96, v250
	v_fmac_f32_e32 v52, v97, v44
	v_fmac_f32_e32 v243, v98, v251
	v_fmac_f32_e32 v53, v99, v45
	v_fmac_f32_e32 v244, v100, v176
	v_fmac_f32_e32 v54, v101, v46
	v_fmac_f32_e32 v245, v102, v177
	v_fmac_f32_e32 v55, v103, v47
	v_add_u32_e32 v181, 0x800000, v1
	v_mov_b32_e32 v120, v238
	v_mov_b32_e32 v121, v48
	v_mov_b32_e32 v122, v239
	v_mov_b32_e32 v123, v49
	global_store_dwordx4 v181, v[120:123], s[10:11] offset:0
	v_mov_b32_e32 v124, v240
	v_mov_b32_e32 v125, v50
	v_mov_b32_e32 v126, v241
	v_mov_b32_e32 v127, v51
	global_store_dwordx4 v181, v[124:127], s[10:11] offset:1024
	v_mov_b32_e32 v150, v242
	v_mov_b32_e32 v151, v52
	v_mov_b32_e32 v152, v243
	v_mov_b32_e32 v153, v53
	global_store_dwordx4 v181, v[150:153], s[10:11] offset:2048
	v_mov_b32_e32 v154, v244
	v_mov_b32_e32 v155, v54
	v_mov_b32_e32 v156, v245
	v_mov_b32_e32 v157, v55
	global_store_dwordx4 v181, v[154:157], s[10:11] offset:3072
	s_waitcnt vmcnt(20)
	v_lshlrev_b32_e32 v246, 16, v8
	v_and_b32_e32 v8, 0xffff0000, v8
	v_lshlrev_b32_e32 v247, 16, v9
	v_and_b32_e32 v9, 0xffff0000, v9
	v_lshlrev_b32_e32 v248, 16, v10
	v_and_b32_e32 v10, 0xffff0000, v10
	v_lshlrev_b32_e32 v249, 16, v11
	v_and_b32_e32 v11, 0xffff0000, v11
	v_lshlrev_b32_e32 v250, 16, v12
	v_and_b32_e32 v12, 0xffff0000, v12
	v_lshlrev_b32_e32 v251, 16, v13
	v_and_b32_e32 v13, 0xffff0000, v13
	v_lshlrev_b32_e32 v176, 16, v14
	v_and_b32_e32 v14, 0xffff0000, v14
	v_lshlrev_b32_e32 v177, 16, v15
	v_and_b32_e32 v15, 0xffff0000, v15
	v_mul_f32_e32 v178, v246, v246
	v_fmac_f32_e32 v178, v8, v8
	v_fmac_f32_e32 v178, v247, v247
	v_fmac_f32_e32 v178, v9, v9
	v_fmac_f32_e32 v178, v248, v248
	v_fmac_f32_e32 v178, v10, v10
	v_fmac_f32_e32 v178, v249, v249
	v_fmac_f32_e32 v178, v11, v11
	v_fmac_f32_e32 v178, v250, v250
	v_fmac_f32_e32 v178, v12, v12
	v_fmac_f32_e32 v178, v251, v251
	v_fmac_f32_e32 v178, v13, v13
	v_fmac_f32_e32 v178, v176, v176
	v_fmac_f32_e32 v178, v14, v14
	v_fmac_f32_e32 v178, v177, v177
	v_fmac_f32_e32 v178, v15, v15
	s_waitcnt vmcnt(16)
	v_lshlrev_b32_e32 v238, 16, v16
	v_and_b32_e32 v16, 0xffff0000, v16
	v_add_f32_dpp v178, v178, v178 quad_perm:[1,0,3,2] row_mask:0xf bank_mask:0xf bound_ctrl:1
	v_lshlrev_b32_e32 v239, 16, v17
	v_and_b32_e32 v17, 0xffff0000, v17
	v_add_f32_dpp v178, v178, v178 quad_perm:[2,3,0,1] row_mask:0xf bank_mask:0xf bound_ctrl:1
	v_lshlrev_b32_e32 v240, 16, v18
	v_and_b32_e32 v18, 0xffff0000, v18
	v_add_f32_dpp v178, v178, v178 row_half_mirror row_mask:0xf bank_mask:0xf bound_ctrl:1
	v_lshlrev_b32_e32 v241, 16, v19
	v_and_b32_e32 v19, 0xffff0000, v19
	v_add_f32_dpp v178, v178, v178 row_mirror row_mask:0xf bank_mask:0xf bound_ctrl:1
	v_lshlrev_b32_e32 v242, 16, v20
	v_and_b32_e32 v20, 0xffff0000, v20
	v_add_f32_dpp v178, v178, v178 row_bcast:15 row_mask:0xa bank_mask:0xf
	v_lshlrev_b32_e32 v243, 16, v21
	v_and_b32_e32 v21, 0xffff0000, v21
	v_add_f32_dpp v178, v178, v178 row_bcast:31 row_mask:0xc bank_mask:0xf
	v_lshlrev_b32_e32 v244, 16, v22
	v_and_b32_e32 v22, 0xffff0000, v22
	v_lshlrev_b32_e32 v245, 16, v23
	v_and_b32_e32 v23, 0xffff0000, v23
	v_readlane_b32 s0, v178, 63
	s_nop 1
	v_mov_b32_e32 v181, s0
	v_fmamk_f32 v181, v181, 0x3a800000, v161
	v_rsq_f32_e32 v179, v181
	s_nop 0
	v_mul_f32_e32 v246, v246, v179
	v_mul_f32_e32 v8, v8, v179
	v_mul_f32_e32 v247, v247, v179
	v_mul_f32_e32 v9, v9, v179
	v_mul_f32_e32 v248, v248, v179
	v_mul_f32_e32 v10, v10, v179
	v_mul_f32_e32 v249, v249, v179
	v_mul_f32_e32 v11, v11, v179
	v_mul_f32_e32 v250, v250, v179
	v_mul_f32_e32 v12, v12, v179
	v_mul_f32_e32 v251, v251, v179
	v_mul_f32_e32 v13, v13, v179
	v_mul_f32_e32 v176, v176, v179
	v_mul_f32_e32 v14, v14, v179
	v_mul_f32_e32 v177, v177, v179
	v_mul_f32_e32 v15, v15, v179
	v_fmac_f32_e32 v238, v88, v246
	v_fmac_f32_e32 v16, v89, v8
	v_fmac_f32_e32 v239, v90, v247
	v_fmac_f32_e32 v17, v91, v9
	v_fmac_f32_e32 v240, v92, v248
	v_fmac_f32_e32 v18, v93, v10
	v_fmac_f32_e32 v241, v94, v249
	v_fmac_f32_e32 v19, v95, v11
	v_fmac_f32_e32 v242, v96, v250
	v_fmac_f32_e32 v20, v97, v12
	v_fmac_f32_e32 v243, v98, v251
	v_fmac_f32_e32 v21, v99, v13
	v_fmac_f32_e32 v244, v100, v176
	v_fmac_f32_e32 v22, v101, v14
	v_fmac_f32_e32 v245, v102, v177
	v_fmac_f32_e32 v23, v103, v15
	v_add_u32_e32 v181, 0x1000000, v1
	v_mov_b32_e32 v120, v238
	v_mov_b32_e32 v121, v16
	v_mov_b32_e32 v122, v239
	v_mov_b32_e32 v123, v17
	global_store_dwordx4 v181, v[120:123], s[10:11] offset:0
	v_mov_b32_e32 v124, v240
	v_mov_b32_e32 v125, v18
	v_mov_b32_e32 v126, v241
	v_mov_b32_e32 v127, v19
	global_store_dwordx4 v181, v[124:127], s[10:11] offset:1024
	v_mov_b32_e32 v150, v242
	v_mov_b32_e32 v151, v20
	v_mov_b32_e32 v152, v243
	v_mov_b32_e32 v153, v21
	global_store_dwordx4 v181, v[150:153], s[10:11] offset:2048
	v_mov_b32_e32 v154, v244
	v_mov_b32_e32 v155, v22
	v_mov_b32_e32 v156, v245
	v_mov_b32_e32 v157, v23
	global_store_dwordx4 v181, v[154:157], s[10:11] offset:3072
	s_waitcnt vmcnt(16)
	v_lshlrev_b32_e32 v246, 16, v190
	v_and_b32_e32 v190, 0xffff0000, v190
	v_lshlrev_b32_e32 v247, 16, v191
	v_and_b32_e32 v191, 0xffff0000, v191
	v_lshlrev_b32_e32 v248, 16, v192
	v_and_b32_e32 v192, 0xffff0000, v192
	v_lshlrev_b32_e32 v249, 16, v193
	v_and_b32_e32 v193, 0xffff0000, v193
	v_lshlrev_b32_e32 v250, 16, v194
	v_and_b32_e32 v194, 0xffff0000, v194
	v_lshlrev_b32_e32 v251, 16, v195
	v_and_b32_e32 v195, 0xffff0000, v195
	v_lshlrev_b32_e32 v176, 16, v196
	v_and_b32_e32 v196, 0xffff0000, v196
	v_lshlrev_b32_e32 v177, 16, v197
	v_and_b32_e32 v197, 0xffff0000, v197
	v_mul_f32_e32 v178, v246, v246
	v_fmac_f32_e32 v178, v190, v190
	v_fmac_f32_e32 v178, v247, v247
	v_fmac_f32_e32 v178, v191, v191
	v_fmac_f32_e32 v178, v248, v248
	v_fmac_f32_e32 v178, v192, v192
	v_fmac_f32_e32 v178, v249, v249
	v_fmac_f32_e32 v178, v193, v193
	v_fmac_f32_e32 v178, v250, v250
	v_fmac_f32_e32 v178, v194, v194
	v_fmac_f32_e32 v178, v251, v251
	v_fmac_f32_e32 v178, v195, v195
	v_fmac_f32_e32 v178, v176, v176
	v_fmac_f32_e32 v178, v196, v196
	v_fmac_f32_e32 v178, v177, v177
	v_fmac_f32_e32 v178, v197, v197
	s_waitcnt vmcnt(12)
	v_lshlrev_b32_e32 v238, 16, v198
	v_and_b32_e32 v198, 0xffff0000, v198
	v_add_f32_dpp v178, v178, v178 quad_perm:[1,0,3,2] row_mask:0xf bank_mask:0xf bound_ctrl:1
	v_lshlrev_b32_e32 v239, 16, v199
	v_and_b32_e32 v199, 0xffff0000, v199
	v_add_f32_dpp v178, v178, v178 quad_perm:[2,3,0,1] row_mask:0xf bank_mask:0xf bound_ctrl:1
	v_lshlrev_b32_e32 v240, 16, v200
	v_and_b32_e32 v200, 0xffff0000, v200
	v_add_f32_dpp v178, v178, v178 row_half_mirror row_mask:0xf bank_mask:0xf bound_ctrl:1
	v_lshlrev_b32_e32 v241, 16, v201
	v_and_b32_e32 v201, 0xffff0000, v201
	v_add_f32_dpp v178, v178, v178 row_mirror row_mask:0xf bank_mask:0xf bound_ctrl:1
	v_lshlrev_b32_e32 v242, 16, v202
	v_and_b32_e32 v202, 0xffff0000, v202
	v_add_f32_dpp v178, v178, v178 row_bcast:15 row_mask:0xa bank_mask:0xf
	v_lshlrev_b32_e32 v243, 16, v203
	v_and_b32_e32 v203, 0xffff0000, v203
	v_add_f32_dpp v178, v178, v178 row_bcast:31 row_mask:0xc bank_mask:0xf
	v_lshlrev_b32_e32 v244, 16, v204
	v_and_b32_e32 v204, 0xffff0000, v204
	v_lshlrev_b32_e32 v245, 16, v205
	v_and_b32_e32 v205, 0xffff0000, v205
	v_readlane_b32 s0, v178, 63
	s_nop 1
	v_mov_b32_e32 v181, s0
	v_fmamk_f32 v181, v181, 0x3a800000, v161
	v_rsq_f32_e32 v179, v181
	s_nop 0
	v_mul_f32_e32 v246, v246, v179
	v_mul_f32_e32 v190, v190, v179
	v_mul_f32_e32 v247, v247, v179
	v_mul_f32_e32 v191, v191, v179
	v_mul_f32_e32 v248, v248, v179
	v_mul_f32_e32 v192, v192, v179
	v_mul_f32_e32 v249, v249, v179
	v_mul_f32_e32 v193, v193, v179
	v_mul_f32_e32 v250, v250, v179
	v_mul_f32_e32 v194, v194, v179
	v_mul_f32_e32 v251, v251, v179
	v_mul_f32_e32 v195, v195, v179
	v_mul_f32_e32 v176, v176, v179
	v_mul_f32_e32 v196, v196, v179
	v_mul_f32_e32 v177, v177, v179
	v_mul_f32_e32 v197, v197, v179
	v_fmac_f32_e32 v238, v88, v246
	v_fmac_f32_e32 v198, v89, v190
	v_fmac_f32_e32 v239, v90, v247
	v_fmac_f32_e32 v199, v91, v191
	v_fmac_f32_e32 v240, v92, v248
	v_fmac_f32_e32 v200, v93, v192
	v_fmac_f32_e32 v241, v94, v249
	v_fmac_f32_e32 v201, v95, v193
	v_fmac_f32_e32 v242, v96, v250
	v_fmac_f32_e32 v202, v97, v194
	v_fmac_f32_e32 v243, v98, v251
	v_fmac_f32_e32 v203, v99, v195
	v_fmac_f32_e32 v244, v100, v176
	v_fmac_f32_e32 v204, v101, v196
	v_fmac_f32_e32 v245, v102, v177
	v_fmac_f32_e32 v205, v103, v197
	v_add_u32_e32 v181, 0x1800000, v1
	v_mov_b32_e32 v120, v238
	v_mov_b32_e32 v121, v198
	v_mov_b32_e32 v122, v239
	v_mov_b32_e32 v123, v199
	global_store_dwordx4 v181, v[120:123], s[10:11] offset:0
	v_mov_b32_e32 v124, v240
	v_mov_b32_e32 v125, v200
	v_mov_b32_e32 v126, v241
	v_mov_b32_e32 v127, v201
	global_store_dwordx4 v181, v[124:127], s[10:11] offset:1024
	v_mov_b32_e32 v150, v242
	v_mov_b32_e32 v151, v202
	v_mov_b32_e32 v152, v243
	v_mov_b32_e32 v153, v203
	global_store_dwordx4 v181, v[150:153], s[10:11] offset:2048
	v_mov_b32_e32 v154, v244
	v_mov_b32_e32 v155, v204
	v_mov_b32_e32 v156, v245
	v_mov_b32_e32 v157, v205
	global_store_dwordx4 v181, v[154:157], s[10:11] offset:3072
	s_branch .LBB0_100

.LBB0_168:
	s_andn2_b64 vcc, exec, s[4:5]
	s_cbranch_vccnz .LBB0_213
	v_readlane_b32 s0, v254, 40
	s_cmp_gt_i32 s0, 4
	s_mov_b64 s[0:1], -1
	s_cbranch_scc0 .LBB0_190
	v_readfirstlane_b32 s0, v160
	v_readlane_b32 s1, v252, 7
	s_lshr_b32 s0, s0, 6
	s_mov_b32 s73, s0
	s_add_i32 s0, s0, s1
	v_readlane_b32 s62, v254, 34
	s_sub_u32 s64, s78, 0x110
	s_subb_u32 s65, s79, 0
	s_load_dwordx2 s[66:67], s[64:65], 0x40
	s_load_dwordx2 s[10:11], s[64:65], 0xf8
	s_lshl_b32 s63, s0, 11
	s_add_u32 s4, s84, 0x167ca000
	s_addc_u32 s5, s85, 0
	s_add_u32 s4, s4, s63
	s_addc_u32 s5, s5, 0
	s_add_u32 s6, s84, 0x112ca000
	s_addc_u32 s7, s85, 0
	s_add_u32 s6, s6, s63
	s_addc_u32 s7, s7, 0
	v_and_b32_e32 v0, 63, v160
	v_lshlrev_b32_e32 v1, 4, v0
	v_lshlrev_b32_e32 v0, 3, v0
	v_add_u32_e32 v2, 0x400000, v0
	v_add_u32_e32 v3, 0x800000, v0
	v_add_u32_e32 v4, 0xc00000, v0
	v_add_u32_e32 v5, 0x1000000, v0
	global_load_dwordx2 v[8:9], v5, s[6:7] offset:0 nt
	global_load_dwordx2 v[10:11], v5, s[6:7] offset:512 nt
	global_load_dwordx2 v[12:13], v5, s[6:7] offset:1024 nt
	global_load_dwordx2 v[14:15], v5, s[6:7] offset:1536 nt
	global_load_dwordx2 v[16:17], v5, s[4:5] offset:0 nt
	global_load_dwordx2 v[18:19], v5, s[4:5] offset:512 nt
	global_load_dwordx2 v[20:21], v5, s[4:5] offset:1024 nt
	global_load_dwordx2 v[22:23], v5, s[4:5] offset:1536 nt
	s_add_u32 s8, s84, 0xaeca000
	s_addc_u32 s9, s85, 0
	s_add_u32 s8, s8, s63
	s_addc_u32 s9, s9, 0
	s_lshr_b32 s69, s0, 10
	s_add_i32 s69, s69, 1
	s_mul_i32 s69, s69, 0x6000
	s_mul_i32 s68, s62, 0x12000
	s_lshl_b32 s72, s62, 14
	s_add_i32 s70, s72, 0x2000
	s_add_i32 s72, s72, 0x1000
	s_add_u32 s16, s84, 0x6602000
	s_addc_u32 s17, s85, 0
	s_add_u32 s16, s16, s68
	s_addc_u32 s17, s17, 0
	s_add_u32 s20, s16, 0x1000
	s_addc_u32 s21, s17, 0
	s_add_u32 s18, s16, 0x2000
	s_addc_u32 s19, s17, 0
	s_add_u32 s22, s16, s69
	s_addc_u32 s23, s17, 0
	s_add_u32 s60, s20, s69
	s_addc_u32 s61, s21, 0
	s_add_u32 s26, s18, s69
	s_addc_u32 s27, s19, 0
	s_lshl_b32 s63, s63, 1
	s_waitcnt lgkmcnt(0)
	s_add_u32 s12, s66, s72
	s_addc_u32 s13, s67, 0
	s_add_u32 s14, s66, s70
	s_addc_u32 s15, s67, 0
	s_add_u32 s10, s10, s63
	s_addc_u32 s11, s11, 0
	s_mov_b64 s[74:75], s[12:13]
	s_cmp_eq_u32 s73, 1
	s_cselect_b32 s74, s14, s74
	s_cselect_b32 s75, s15, s75
	s_cmp_eq_u32 s73, 2
	s_cselect_b32 s74, s16, s74
	s_cselect_b32 s75, s17, s75
	s_cmp_eq_u32 s73, 3
	s_cselect_b32 s74, s18, s74
	s_cselect_b32 s75, s19, s75
	s_cmp_eq_u32 s73, 4
	s_cselect_b32 s74, s20, s74
	s_cselect_b32 s75, s21, s75
	s_cmp_eq_u32 s73, 5
	s_cselect_b32 s74, s22, s74
	s_cselect_b32 s75, s23, s75
	s_cmp_eq_u32 s73, 6
	s_cselect_b32 s74, s26, s74
	s_cselect_b32 s75, s27, s75
	s_cmp_eq_u32 s73, 7
	s_cselect_b32 s74, s60, s74
	s_cselect_b32 s75, s61, s75
	global_load_dwordx4 v[222:225], v1, s[74:75] offset:0
	global_load_dwordx4 v[226:229], v1, s[74:75] offset:1024
	global_load_dwordx4 v[230:233], v1, s[74:75] offset:2048
	global_load_dwordx4 v[234:237], v1, s[74:75] offset:3072
	s_lshl_b32 s74, s73, 12
	v_add_u32_e32 v6, s74, v1
	global_load_dwordx2 v[24:25], v0, s[6:7] offset:0 nt
	global_load_dwordx2 v[26:27], v0, s[6:7] offset:512 nt
	global_load_dwordx2 v[28:29], v0, s[6:7] offset:1024 nt
	global_load_dwordx2 v[30:31], v0, s[6:7] offset:1536 nt
	global_load_dwordx2 v[32:33], v0, s[4:5] offset:0 nt
	global_load_dwordx2 v[34:35], v0, s[4:5] offset:512 nt
	global_load_dwordx2 v[36:37], v0, s[4:5] offset:1024 nt
	global_load_dwordx2 v[38:39], v0, s[4:5] offset:1536 nt
	global_load_dwordx2 v[40:41], v2, s[6:7] offset:0 nt
	global_load_dwordx2 v[42:43], v2, s[6:7] offset:512 nt
	global_load_dwordx2 v[44:45], v2, s[6:7] offset:1024 nt
	global_load_dwordx2 v[46:47], v2, s[6:7] offset:1536 nt
	global_load_dwordx2 v[48:49], v2, s[4:5] offset:0 nt
	global_load_dwordx2 v[50:51], v2, s[4:5] offset:512 nt
	global_load_dwordx2 v[52:53], v2, s[4:5] offset:1024 nt
	global_load_dwordx2 v[54:55], v2, s[4:5] offset:1536 nt
	s_waitcnt vmcnt(16)
	ds_write_b128 v6, v[222:225] offset:0
	ds_write_b128 v6, v[226:229] offset:1024
	ds_write_b128 v6, v[230:233] offset:2048
	ds_write_b128 v6, v[234:237] offset:3072
	s_waitcnt lgkmcnt(0)
	s_barrier
	ds_read_b128 v[56:59], v1 offset:0
	ds_read_b128 v[60:63], v1 offset:1024
	ds_read_b128 v[64:67], v1 offset:2048
	ds_read_b128 v[68:71], v1 offset:3072
	ds_read_b128 v[72:75], v1 offset:4096
	ds_read_b128 v[76:79], v1 offset:5120
	ds_read_b128 v[80:83], v1 offset:6144
	ds_read_b128 v[84:87], v1 offset:7168
	ds_read_b128 v[88:91], v1 offset:8192
	ds_read_b128 v[92:95], v1 offset:9216
	ds_read_b128 v[96:99], v1 offset:10240
	ds_read_b128 v[100:103], v1 offset:11264
	ds_read_b128 v[104:107], v1 offset:12288
	ds_read_b128 v[108:111], v1 offset:13312
	ds_read_b128 v[112:115], v1 offset:14336
	ds_read_b128 v[116:119], v1 offset:15360
	ds_read_b128 v[134:137], v1 offset:16384
	ds_read_b128 v[138:141], v1 offset:17408
	ds_read_b128 v[142:145], v1 offset:18432
	ds_read_b128 v[146:149], v1 offset:19456
	ds_read_b128 v[190:193], v1 offset:20480
	ds_read_b128 v[194:197], v1 offset:21504
	ds_read_b128 v[198:201], v1 offset:22528
	ds_read_b128 v[202:205], v1 offset:23552
	ds_read_b128 v[206:209], v1 offset:24576
	ds_read_b128 v[210:213], v1 offset:25600
	ds_read_b128 v[214:217], v1 offset:26624
	ds_read_b128 v[218:221], v1 offset:27648
	ds_read_b128 v[222:225], v1 offset:28672
	ds_read_b128 v[226:229], v1 offset:29696
	ds_read_b128 v[230:233], v1 offset:30720
	ds_read_b128 v[234:237], v1 offset:31744
	v_lshlrev_b32_e32 v246, 16, v8
	v_and_b32_e32 v8, 0xffff0000, v8
	v_lshlrev_b32_e32 v247, 16, v9
	v_and_b32_e32 v9, 0xffff0000, v9
	v_lshlrev_b32_e32 v248, 16, v10
	v_and_b32_e32 v10, 0xffff0000, v10
	v_lshlrev_b32_e32 v249, 16, v11
	v_and_b32_e32 v11, 0xffff0000, v11
	v_lshlrev_b32_e32 v250, 16, v12
	v_and_b32_e32 v12, 0xffff0000, v12
	v_lshlrev_b32_e32 v251, 16, v13
	v_and_b32_e32 v13, 0xffff0000, v13
	v_lshlrev_b32_e32 v176, 16, v14
	v_and_b32_e32 v14, 0xffff0000, v14
	v_lshlrev_b32_e32 v177, 16, v15
	v_and_b32_e32 v15, 0xffff0000, v15
	v_mul_f32_e32 v178, v246, v246
	v_fmac_f32_e32 v178, v8, v8
	v_fmac_f32_e32 v178, v247, v247
	v_fmac_f32_e32 v178, v9, v9
	v_fmac_f32_e32 v178, v248, v248
	v_fmac_f32_e32 v178, v10, v10
	v_fmac_f32_e32 v178, v249, v249
	v_fmac_f32_e32 v178, v11, v11
	v_fmac_f32_e32 v178, v250, v250
	v_fmac_f32_e32 v178, v12, v12
	v_fmac_f32_e32 v178, v251, v251
	v_fmac_f32_e32 v178, v13, v13
	v_fmac_f32_e32 v178, v176, v176
	v_fmac_f32_e32 v178, v14, v14
	v_fmac_f32_e32 v178, v177, v177
	v_fmac_f32_e32 v178, v15, v15
	v_lshlrev_b32_e32 v238, 16, v16
	v_and_b32_e32 v16, 0xffff0000, v16
	v_add_f32_dpp v178, v178, v178 quad_perm:[1,0,3,2] row_mask:0xf bank_mask:0xf bound_ctrl:1
	v_lshlrev_b32_e32 v239, 16, v17
	v_and_b32_e32 v17, 0xffff0000, v17
	v_add_f32_dpp v178, v178, v178 quad_perm:[2,3,0,1] row_mask:0xf bank_mask:0xf bound_ctrl:1
	v_lshlrev_b32_e32 v240, 16, v18
	v_and_b32_e32 v18, 0xffff0000, v18
	v_add_f32_dpp v178, v178, v178 row_half_mirror row_mask:0xf bank_mask:0xf bound_ctrl:1
	v_lshlrev_b32_e32 v241, 16, v19
	v_and_b32_e32 v19, 0xffff0000, v19
	v_add_f32_dpp v178, v178, v178 row_mirror row_mask:0xf bank_mask:0xf bound_ctrl:1
	v_lshlrev_b32_e32 v242, 16, v20
	v_and_b32_e32 v20, 0xffff0000, v20
	v_add_f32_dpp v178, v178, v178 row_bcast:15 row_mask:0xa bank_mask:0xf
	v_lshlrev_b32_e32 v243, 16, v21
	v_and_b32_e32 v21, 0xffff0000, v21
	v_add_f32_dpp v178, v178, v178 row_bcast:31 row_mask:0xc bank_mask:0xf
	v_lshlrev_b32_e32 v244, 16, v22
	v_and_b32_e32 v22, 0xffff0000, v22
	v_lshlrev_b32_e32 v245, 16, v23
	v_and_b32_e32 v23, 0xffff0000, v23
	v_readlane_b32 s0, v178, 63
	s_nop 1
	v_mov_b32_e32 v181, s0
	v_fmamk_f32 v181, v181, 0x3a800000, v161
	v_rsq_f32_e32 v179, v181
	s_nop 0
	s_waitcnt lgkmcnt(0)
	v_mul_f32_e32 v190, v190, v56
	v_mul_f32_e32 v191, v191, v57
	v_mul_f32_e32 v192, v192, v58
	v_mul_f32_e32 v193, v193, v59
	v_mul_f32_e32 v194, v194, v60
	v_mul_f32_e32 v195, v195, v61
	v_mul_f32_e32 v196, v196, v62
	v_mul_f32_e32 v197, v197, v63
	v_mul_f32_e32 v198, v198, v64
	v_mul_f32_e32 v199, v199, v65
	v_mul_f32_e32 v200, v200, v66
	v_mul_f32_e32 v201, v201, v67
	v_mul_f32_e32 v202, v202, v68
	v_mul_f32_e32 v203, v203, v69
	v_mul_f32_e32 v204, v204, v70
	v_mul_f32_e32 v205, v205, v71
	v_mul_f32_e32 v88, v88, v56
	v_mul_f32_e32 v89, v89, v57
	v_mul_f32_e32 v90, v90, v58
	v_mul_f32_e32 v91, v91, v59
	v_mul_f32_e32 v92, v92, v60
	v_mul_f32_e32 v93, v93, v61
	v_mul_f32_e32 v94, v94, v62
	v_mul_f32_e32 v95, v95, v63
	v_mul_f32_e32 v96, v96, v64
	v_mul_f32_e32 v97, v97, v65
	v_mul_f32_e32 v98, v98, v66
	v_mul_f32_e32 v99, v99, v67
	v_mul_f32_e32 v100, v100, v68
	v_mul_f32_e32 v101, v101, v69
	v_mul_f32_e32 v102, v102, v70
	v_mul_f32_e32 v103, v103, v71
	v_mul_f32_e32 v246, v246, v179
	v_mul_f32_e32 v8, v8, v179
	v_mul_f32_e32 v247, v247, v179
	v_mul_f32_e32 v9, v9, v179
	v_mul_f32_e32 v248, v248, v179
	v_mul_f32_e32 v10, v10, v179
	v_mul_f32_e32 v249, v249, v179
	v_mul_f32_e32 v11, v11, v179
	v_mul_f32_e32 v250, v250, v179
	v_mul_f32_e32 v12, v12, v179
	v_mul_f32_e32 v251, v251, v179
	v_mul_f32_e32 v13, v13, v179
	v_mul_f32_e32 v176, v176, v179
	v_mul_f32_e32 v14, v14, v179
	v_mul_f32_e32 v177, v177, v179
	v_mul_f32_e32 v15, v15, v179
	v_fmac_f32_e32 v238, v190, v246
	v_fmac_f32_e32 v16, v191, v8
	v_fmac_f32_e32 v239, v192, v247
	v_fmac_f32_e32 v17, v193, v9
	v_fmac_f32_e32 v240, v194, v248
	v_fmac_f32_e32 v18, v195, v10
	v_fmac_f32_e32 v241, v196, v249
	v_fmac_f32_e32 v19, v197, v11
	v_fmac_f32_e32 v242, v198, v250
	v_fmac_f32_e32 v20, v199, v12
	v_fmac_f32_e32 v243, v200, v251
	v_fmac_f32_e32 v21, v201, v13
	v_fmac_f32_e32 v244, v202, v176
	v_fmac_f32_e32 v22, v203, v14
	v_fmac_f32_e32 v245, v204, v177
	v_fmac_f32_e32 v23, v205, v15
	v_cvt_pk_bf16_f32 v120, v238, v16
	v_cvt_pk_bf16_f32 v121, v239, v17
	global_store_dwordx2 v5, v[120:121], s[4:5] offset:0 nt
	v_cvt_pk_bf16_f32 v122, v240, v18
	v_cvt_pk_bf16_f32 v123, v241, v19
	global_store_dwordx2 v5, v[122:123], s[4:5] offset:512 nt
	v_cvt_pk_bf16_f32 v124, v242, v20
	v_cvt_pk_bf16_f32 v125, v243, v21
	global_store_dwordx2 v5, v[124:125], s[4:5] offset:1024 nt
	v_cvt_pk_bf16_f32 v126, v244, v22
	v_cvt_pk_bf16_f32 v127, v245, v23
	global_store_dwordx2 v5, v[126:127], s[4:5] offset:1536 nt
	v_mul_f32_e32 v178, v238, v238
	v_fmac_f32_e32 v178, v16, v16
	v_fmac_f32_e32 v178, v239, v239
	v_fmac_f32_e32 v178, v17, v17
	v_fmac_f32_e32 v178, v240, v240
	v_fmac_f32_e32 v178, v18, v18
	v_fmac_f32_e32 v178, v241, v241
	v_fmac_f32_e32 v178, v19, v19
	v_fmac_f32_e32 v178, v242, v242
	v_fmac_f32_e32 v178, v20, v20
	v_fmac_f32_e32 v178, v243, v243
	v_fmac_f32_e32 v178, v21, v21
	v_fmac_f32_e32 v178, v244, v244
	v_fmac_f32_e32 v178, v22, v22
	v_fmac_f32_e32 v178, v245, v245
	v_fmac_f32_e32 v178, v23, v23
	v_add_f32_e32 v206, 1.0, v206
	v_add_f32_e32 v207, 1.0, v207
	v_add_f32_dpp v178, v178, v178 quad_perm:[1,0,3,2] row_mask:0xf bank_mask:0xf bound_ctrl:1
	v_add_f32_e32 v208, 1.0, v208
	v_add_f32_e32 v209, 1.0, v209
	v_add_f32_dpp v178, v178, v178 quad_perm:[2,3,0,1] row_mask:0xf bank_mask:0xf bound_ctrl:1
	v_add_f32_e32 v210, 1.0, v210
	v_add_f32_e32 v211, 1.0, v211
	v_add_f32_dpp v178, v178, v178 row_half_mirror row_mask:0xf bank_mask:0xf bound_ctrl:1
	v_add_f32_e32 v212, 1.0, v212
	v_add_f32_e32 v213, 1.0, v213
	v_add_f32_dpp v178, v178, v178 row_mirror row_mask:0xf bank_mask:0xf bound_ctrl:1
	v_add_f32_e32 v214, 1.0, v214
	v_add_f32_e32 v215, 1.0, v215
	v_add_f32_dpp v178, v178, v178 row_bcast:15 row_mask:0xa bank_mask:0xf
	v_add_f32_e32 v216, 1.0, v216
	v_add_f32_e32 v217, 1.0, v217
	v_add_f32_dpp v178, v178, v178 row_bcast:31 row_mask:0xc bank_mask:0xf
	v_add_f32_e32 v218, 1.0, v218
	v_add_f32_e32 v219, 1.0, v219
	v_add_f32_e32 v220, 1.0, v220
	v_add_f32_e32 v221, 1.0, v221
	v_mul_f32_e32 v206, v206, v72
	v_mul_f32_e32 v207, v207, v73
	v_mul_f32_e32 v208, v208, v74
	v_mul_f32_e32 v209, v209, v75
	v_mul_f32_e32 v210, v210, v76
	v_mul_f32_e32 v211, v211, v77
	v_mul_f32_e32 v212, v212, v78
	v_mul_f32_e32 v213, v213, v79
	v_mul_f32_e32 v214, v214, v80
	v_mul_f32_e32 v215, v215, v81
	v_mul_f32_e32 v216, v216, v82
	v_mul_f32_e32 v217, v217, v83
	v_mul_f32_e32 v218, v218, v84
	v_mul_f32_e32 v219, v219, v85
	v_mul_f32_e32 v220, v220, v86
	v_mul_f32_e32 v221, v221, v87
	v_readlane_b32 s0, v178, 63
	s_nop 1
	v_mov_b32_e32 v181, s0
	v_fmamk_f32 v181, v181, 0x3a800000, v161
	v_rsq_f32_e32 v180, v181
	s_nop 0
	v_mul_f32_e32 v238, v238, v180
	v_mul_f32_e32 v16, v16, v180
	v_mul_f32_e32 v239, v239, v180
	v_mul_f32_e32 v17, v17, v180
	v_mul_f32_e32 v240, v240, v180
	v_mul_f32_e32 v18, v18, v180
	v_mul_f32_e32 v241, v241, v180
	v_mul_f32_e32 v19, v19, v180
	v_mul_f32_e32 v242, v242, v180
	v_mul_f32_e32 v20, v20, v180
	v_mul_f32_e32 v243, v243, v180
	v_mul_f32_e32 v21, v21, v180
	v_mul_f32_e32 v244, v244, v180
	v_mul_f32_e32 v22, v22, v180
	v_mul_f32_e32 v245, v245, v180
	v_mul_f32_e32 v23, v23, v180
	v_fma_f32 v238, v238, v206, v222
	v_fma_f32 v16, v16, v207, v223
	v_fma_f32 v239, v239, v208, v224
	v_fma_f32 v17, v17, v209, v225
	v_fma_f32 v240, v240, v210, v226
	v_fma_f32 v18, v18, v211, v227
	v_fma_f32 v241, v241, v212, v228
	v_fma_f32 v19, v19, v213, v229
	v_fma_f32 v242, v242, v214, v230
	v_fma_f32 v20, v20, v215, v231
	v_fma_f32 v243, v243, v216, v232
	v_fma_f32 v21, v21, v217, v233
	v_fma_f32 v244, v244, v218, v234
	v_fma_f32 v22, v22, v219, v235
	v_fma_f32 v245, v245, v220, v236
	v_fma_f32 v23, v23, v221, v237
	v_cvt_pk_bf16_f32 v150, v238, v16
	v_cvt_pk_bf16_f32 v151, v239, v17
	global_store_dwordx2 v5, v[150:151], s[8:9] offset:0
	v_cvt_pk_bf16_f32 v152, v240, v18
	v_cvt_pk_bf16_f32 v153, v241, v19
	global_store_dwordx2 v5, v[152:153], s[8:9] offset:512
	v_cvt_pk_bf16_f32 v154, v242, v20
	v_cvt_pk_bf16_f32 v155, v243, v21
	global_store_dwordx2 v5, v[154:155], s[8:9] offset:1024
	v_cvt_pk_bf16_f32 v156, v244, v22
	v_cvt_pk_bf16_f32 v157, v245, v23
	global_store_dwordx2 v5, v[156:157], s[8:9] offset:1536
	global_load_dwordx2 v[8:9], v3, s[6:7] offset:0 nt
	global_load_dwordx2 v[10:11], v3, s[6:7] offset:512 nt
	global_load_dwordx2 v[12:13], v3, s[6:7] offset:1024 nt
	global_load_dwordx2 v[14:15], v3, s[6:7] offset:1536 nt
	global_load_dwordx2 v[16:17], v3, s[4:5] offset:0 nt
	global_load_dwordx2 v[18:19], v3, s[4:5] offset:512 nt
	global_load_dwordx2 v[20:21], v3, s[4:5] offset:1024 nt
	global_load_dwordx2 v[22:23], v3, s[4:5] offset:1536 nt
	global_load_dwordx2 v[190:191], v4, s[6:7] offset:0 nt
	global_load_dwordx2 v[192:193], v4, s[6:7] offset:512 nt
	global_load_dwordx2 v[194:195], v4, s[6:7] offset:1024 nt
	global_load_dwordx2 v[196:197], v4, s[6:7] offset:1536 nt
	global_load_dwordx2 v[198:199], v4, s[4:5] offset:0 nt
	global_load_dwordx2 v[200:201], v4, s[4:5] offset:512 nt
	global_load_dwordx2 v[202:203], v4, s[4:5] offset:1024 nt
	global_load_dwordx2 v[204:205], v4, s[4:5] offset:1536 nt
	s_waitcnt vmcnt(36)
	v_lshlrev_b32_e32 v246, 16, v24
	v_and_b32_e32 v24, 0xffff0000, v24
	v_lshlrev_b32_e32 v247, 16, v25
	v_and_b32_e32 v25, 0xffff0000, v25
	v_lshlrev_b32_e32 v248, 16, v26
	v_and_b32_e32 v26, 0xffff0000, v26
	v_lshlrev_b32_e32 v249, 16, v27
	v_and_b32_e32 v27, 0xffff0000, v27
	v_lshlrev_b32_e32 v250, 16, v28
	v_and_b32_e32 v28, 0xffff0000, v28
	v_lshlrev_b32_e32 v251, 16, v29
	v_and_b32_e32 v29, 0xffff0000, v29
	v_lshlrev_b32_e32 v176, 16, v30
	v_and_b32_e32 v30, 0xffff0000, v30
	v_lshlrev_b32_e32 v177, 16, v31
	v_and_b32_e32 v31, 0xffff0000, v31
	v_mul_f32_e32 v178, v246, v246
	v_fmac_f32_e32 v178, v24, v24
	v_fmac_f32_e32 v178, v247, v247
	v_fmac_f32_e32 v178, v25, v25
	v_fmac_f32_e32 v178, v248, v248
	v_fmac_f32_e32 v178, v26, v26
	v_fmac_f32_e32 v178, v249, v249
	v_fmac_f32_e32 v178, v27, v27
	v_fmac_f32_e32 v178, v250, v250
	v_fmac_f32_e32 v178, v28, v28
	v_fmac_f32_e32 v178, v251, v251
	v_fmac_f32_e32 v178, v29, v29
	v_fmac_f32_e32 v178, v176, v176
	v_fmac_f32_e32 v178, v30, v30
	v_fmac_f32_e32 v178, v177, v177
	v_fmac_f32_e32 v178, v31, v31
	s_waitcnt vmcnt(32)
	v_lshlrev_b32_e32 v238, 16, v32
	v_and_b32_e32 v32, 0xffff0000, v32
	v_add_f32_dpp v178, v178, v178 quad_perm:[1,0,3,2] row_mask:0xf bank_mask:0xf bound_ctrl:1
	v_lshlrev_b32_e32 v239, 16, v33
	v_and_b32_e32 v33, 0xffff0000, v33
	v_add_f32_dpp v178, v178, v178 quad_perm:[2,3,0,1] row_mask:0xf bank_mask:0xf bound_ctrl:1
	v_lshlrev_b32_e32 v240, 16, v34
	v_and_b32_e32 v34, 0xffff0000, v34
	v_add_f32_dpp v178, v178, v178 row_half_mirror row_mask:0xf bank_mask:0xf bound_ctrl:1
	v_lshlrev_b32_e32 v241, 16, v35
	v_and_b32_e32 v35, 0xffff0000, v35
	v_add_f32_dpp v178, v178, v178 row_mirror row_mask:0xf bank_mask:0xf bound_ctrl:1
	v_lshlrev_b32_e32 v242, 16, v36
	v_and_b32_e32 v36, 0xffff0000, v36
	v_add_f32_dpp v178, v178, v178 row_bcast:15 row_mask:0xa bank_mask:0xf
	v_lshlrev_b32_e32 v243, 16, v37
	v_and_b32_e32 v37, 0xffff0000, v37
	v_add_f32_dpp v178, v178, v178 row_bcast:31 row_mask:0xc bank_mask:0xf
	v_lshlrev_b32_e32 v244, 16, v38
	v_and_b32_e32 v38, 0xffff0000, v38
	v_lshlrev_b32_e32 v245, 16, v39
	v_and_b32_e32 v39, 0xffff0000, v39
	v_readlane_b32 s0, v178, 63
	s_nop 1
	v_mov_b32_e32 v181, s0
	v_fmamk_f32 v181, v181, 0x3a800000, v161
	v_rsq_f32_e32 v179, v181
	s_nop 0
	v_mul_f32_e32 v246, v246, v179
	v_mul_f32_e32 v24, v24, v179
	v_mul_f32_e32 v247, v247, v179
	v_mul_f32_e32 v25, v25, v179
	v_mul_f32_e32 v248, v248, v179
	v_mul_f32_e32 v26, v26, v179
	v_mul_f32_e32 v249, v249, v179
	v_mul_f32_e32 v27, v27, v179
	v_mul_f32_e32 v250, v250, v179
	v_mul_f32_e32 v28, v28, v179
	v_mul_f32_e32 v251, v251, v179
	v_mul_f32_e32 v29, v29, v179
	v_mul_f32_e32 v176, v176, v179
	v_mul_f32_e32 v30, v30, v179
	v_mul_f32_e32 v177, v177, v179
	v_mul_f32_e32 v31, v31, v179
	v_fmac_f32_e32 v238, v88, v246
	v_fmac_f32_e32 v32, v89, v24
	v_fmac_f32_e32 v239, v90, v247
	v_fmac_f32_e32 v33, v91, v25
	v_fmac_f32_e32 v240, v92, v248
	v_fmac_f32_e32 v34, v93, v26
	v_fmac_f32_e32 v241, v94, v249
	v_fmac_f32_e32 v35, v95, v27
	v_fmac_f32_e32 v242, v96, v250
	v_fmac_f32_e32 v36, v97, v28
	v_fmac_f32_e32 v243, v98, v251
	v_fmac_f32_e32 v37, v99, v29
	v_fmac_f32_e32 v244, v100, v176
	v_fmac_f32_e32 v38, v101, v30
	v_fmac_f32_e32 v245, v102, v177
	v_fmac_f32_e32 v39, v103, v31
	v_cvt_pk_bf16_f32 v120, v238, v32
	v_cvt_pk_bf16_f32 v121, v239, v33
	global_store_dwordx2 v0, v[120:121], s[4:5] offset:0 nt
	v_cvt_pk_bf16_f32 v122, v240, v34
	v_cvt_pk_bf16_f32 v123, v241, v35
	global_store_dwordx2 v0, v[122:123], s[4:5] offset:512 nt
	v_cvt_pk_bf16_f32 v124, v242, v36
	v_cvt_pk_bf16_f32 v125, v243, v37
	global_store_dwordx2 v0, v[124:125], s[4:5] offset:1024 nt
	v_cvt_pk_bf16_f32 v126, v244, v38
	v_cvt_pk_bf16_f32 v127, v245, v39
	global_store_dwordx2 v0, v[126:127], s[4:5] offset:1536 nt
	v_mul_f32_e32 v178, v238, v238
	v_fmac_f32_e32 v178, v32, v32
	v_fmac_f32_e32 v178, v239, v239
	v_fmac_f32_e32 v178, v33, v33
	v_fmac_f32_e32 v178, v240, v240
	v_fmac_f32_e32 v178, v34, v34
	v_fmac_f32_e32 v178, v241, v241
	v_fmac_f32_e32 v178, v35, v35
	v_fmac_f32_e32 v178, v242, v242
	v_fmac_f32_e32 v178, v36, v36
	v_fmac_f32_e32 v178, v243, v243
	v_fmac_f32_e32 v178, v37, v37
	v_fmac_f32_e32 v178, v244, v244
	v_fmac_f32_e32 v178, v38, v38
	v_fmac_f32_e32 v178, v245, v245
	v_fmac_f32_e32 v178, v39, v39
	v_add_f32_e32 v104, 1.0, v104
	v_add_f32_e32 v105, 1.0, v105
	v_add_f32_dpp v178, v178, v178 quad_perm:[1,0,3,2] row_mask:0xf bank_mask:0xf bound_ctrl:1
	v_add_f32_e32 v106, 1.0, v106
	v_add_f32_e32 v107, 1.0, v107
	v_add_f32_dpp v178, v178, v178 quad_perm:[2,3,0,1] row_mask:0xf bank_mask:0xf bound_ctrl:1
	v_add_f32_e32 v108, 1.0, v108
	v_add_f32_e32 v109, 1.0, v109
	v_add_f32_dpp v178, v178, v178 row_half_mirror row_mask:0xf bank_mask:0xf bound_ctrl:1
	v_add_f32_e32 v110, 1.0, v110
	v_add_f32_e32 v111, 1.0, v111
	v_add_f32_dpp v178, v178, v178 row_mirror row_mask:0xf bank_mask:0xf bound_ctrl:1
	v_add_f32_e32 v112, 1.0, v112
	v_add_f32_e32 v113, 1.0, v113
	v_add_f32_dpp v178, v178, v178 row_bcast:15 row_mask:0xa bank_mask:0xf
	v_add_f32_e32 v114, 1.0, v114
	v_add_f32_e32 v115, 1.0, v115
	v_add_f32_dpp v178, v178, v178 row_bcast:31 row_mask:0xc bank_mask:0xf
	v_add_f32_e32 v116, 1.0, v116
	v_add_f32_e32 v117, 1.0, v117
	v_add_f32_e32 v118, 1.0, v118
	v_add_f32_e32 v119, 1.0, v119
	v_mul_f32_e32 v104, v104, v72
	v_mul_f32_e32 v105, v105, v73
	v_mul_f32_e32 v106, v106, v74
	v_mul_f32_e32 v107, v107, v75
	v_mul_f32_e32 v108, v108, v76
	v_mul_f32_e32 v109, v109, v77
	v_mul_f32_e32 v110, v110, v78
	v_mul_f32_e32 v111, v111, v79
	v_mul_f32_e32 v112, v112, v80
	v_mul_f32_e32 v113, v113, v81
	v_mul_f32_e32 v114, v114, v82
	v_mul_f32_e32 v115, v115, v83
	v_mul_f32_e32 v116, v116, v84
	v_mul_f32_e32 v117, v117, v85
	v_mul_f32_e32 v118, v118, v86
	v_mul_f32_e32 v119, v119, v87
	v_readlane_b32 s0, v178, 63
	s_nop 1
	v_mov_b32_e32 v181, s0
	v_fmamk_f32 v181, v181, 0x3a800000, v161
	v_rsq_f32_e32 v180, v181
	s_nop 0
	v_mul_f32_e32 v238, v238, v180
	v_mul_f32_e32 v32, v32, v180
	v_mul_f32_e32 v239, v239, v180
	v_mul_f32_e32 v33, v33, v180
	v_mul_f32_e32 v240, v240, v180
	v_mul_f32_e32 v34, v34, v180
	v_mul_f32_e32 v241, v241, v180
	v_mul_f32_e32 v35, v35, v180
	v_mul_f32_e32 v242, v242, v180
	v_mul_f32_e32 v36, v36, v180
	v_mul_f32_e32 v243, v243, v180
	v_mul_f32_e32 v37, v37, v180
	v_mul_f32_e32 v244, v244, v180
	v_mul_f32_e32 v38, v38, v180
	v_mul_f32_e32 v245, v245, v180
	v_mul_f32_e32 v39, v39, v180
	v_fma_f32 v238, v238, v104, v134
	v_fma_f32 v32, v32, v105, v135
	v_fma_f32 v239, v239, v106, v136
	v_fma_f32 v33, v33, v107, v137
	v_fma_f32 v240, v240, v108, v138
	v_fma_f32 v34, v34, v109, v139
	v_fma_f32 v241, v241, v110, v140
	v_fma_f32 v35, v35, v111, v141
	v_fma_f32 v242, v242, v112, v142
	v_fma_f32 v36, v36, v113, v143
	v_fma_f32 v243, v243, v114, v144
	v_fma_f32 v37, v37, v115, v145
	v_fma_f32 v244, v244, v116, v146
	v_fma_f32 v38, v38, v117, v147
	v_fma_f32 v245, v245, v118, v148
	v_fma_f32 v39, v39, v119, v149
	v_cvt_pk_bf16_f32 v150, v238, v32
	v_cvt_pk_bf16_f32 v151, v239, v33
	global_store_dwordx2 v0, v[150:151], s[8:9] offset:0
	v_cvt_pk_bf16_f32 v152, v240, v34
	v_cvt_pk_bf16_f32 v153, v241, v35
	global_store_dwordx2 v0, v[152:153], s[8:9] offset:512
	v_cvt_pk_bf16_f32 v154, v242, v36
	v_cvt_pk_bf16_f32 v155, v243, v37
	global_store_dwordx2 v0, v[154:155], s[8:9] offset:1024
	v_cvt_pk_bf16_f32 v156, v244, v38
	v_cvt_pk_bf16_f32 v157, v245, v39
	global_store_dwordx2 v0, v[156:157], s[8:9] offset:1536
	s_waitcnt vmcnt(36)
	v_lshlrev_b32_e32 v246, 16, v40
	v_and_b32_e32 v40, 0xffff0000, v40
	v_lshlrev_b32_e32 v247, 16, v41
	v_and_b32_e32 v41, 0xffff0000, v41
	v_lshlrev_b32_e32 v248, 16, v42
	v_and_b32_e32 v42, 0xffff0000, v42
	v_lshlrev_b32_e32 v249, 16, v43
	v_and_b32_e32 v43, 0xffff0000, v43
	v_lshlrev_b32_e32 v250, 16, v44
	v_and_b32_e32 v44, 0xffff0000, v44
	v_lshlrev_b32_e32 v251, 16, v45
	v_and_b32_e32 v45, 0xffff0000, v45
	v_lshlrev_b32_e32 v176, 16, v46
	v_and_b32_e32 v46, 0xffff0000, v46
	v_lshlrev_b32_e32 v177, 16, v47
	v_and_b32_e32 v47, 0xffff0000, v47
	v_mul_f32_e32 v178, v246, v246
	v_fmac_f32_e32 v178, v40, v40
	v_fmac_f32_e32 v178, v247, v247
	v_fmac_f32_e32 v178, v41, v41
	v_fmac_f32_e32 v178, v248, v248
	v_fmac_f32_e32 v178, v42, v42
	v_fmac_f32_e32 v178, v249, v249
	v_fmac_f32_e32 v178, v43, v43
	v_fmac_f32_e32 v178, v250, v250
	v_fmac_f32_e32 v178, v44, v44
	v_fmac_f32_e32 v178, v251, v251
	v_fmac_f32_e32 v178, v45, v45
	v_fmac_f32_e32 v178, v176, v176
	v_fmac_f32_e32 v178, v46, v46
	v_fmac_f32_e32 v178, v177, v177
	v_fmac_f32_e32 v178, v47, v47
	s_waitcnt vmcnt(32)
	v_lshlrev_b32_e32 v238, 16, v48
	v_and_b32_e32 v48, 0xffff0000, v48
	v_add_f32_dpp v178, v178, v178 quad_perm:[1,0,3,2] row_mask:0xf bank_mask:0xf bound_ctrl:1
	v_lshlrev_b32_e32 v239, 16, v49
	v_and_b32_e32 v49, 0xffff0000, v49
	v_add_f32_dpp v178, v178, v178 quad_perm:[2,3,0,1] row_mask:0xf bank_mask:0xf bound_ctrl:1
	v_lshlrev_b32_e32 v240, 16, v50
	v_and_b32_e32 v50, 0xffff0000, v50
	v_add_f32_dpp v178, v178, v178 row_half_mirror row_mask:0xf bank_mask:0xf bound_ctrl:1
	v_lshlrev_b32_e32 v241, 16, v51
	v_and_b32_e32 v51, 0xffff0000, v51
	v_add_f32_dpp v178, v178, v178 row_mirror row_mask:0xf bank_mask:0xf bound_ctrl:1
	v_lshlrev_b32_e32 v242, 16, v52
	v_and_b32_e32 v52, 0xffff0000, v52
	v_add_f32_dpp v178, v178, v178 row_bcast:15 row_mask:0xa bank_mask:0xf
	v_lshlrev_b32_e32 v243, 16, v53
	v_and_b32_e32 v53, 0xffff0000, v53
	v_add_f32_dpp v178, v178, v178 row_bcast:31 row_mask:0xc bank_mask:0xf
	v_lshlrev_b32_e32 v244, 16, v54
	v_and_b32_e32 v54, 0xffff0000, v54
	v_lshlrev_b32_e32 v245, 16, v55
	v_and_b32_e32 v55, 0xffff0000, v55
	v_readlane_b32 s0, v178, 63
	s_nop 1
	v_mov_b32_e32 v181, s0
	v_fmamk_f32 v181, v181, 0x3a800000, v161
	v_rsq_f32_e32 v179, v181
	s_nop 0
	v_mul_f32_e32 v246, v246, v179
	v_mul_f32_e32 v40, v40, v179
	v_mul_f32_e32 v247, v247, v179
	v_mul_f32_e32 v41, v41, v179
	v_mul_f32_e32 v248, v248, v179
	v_mul_f32_e32 v42, v42, v179
	v_mul_f32_e32 v249, v249, v179
	v_mul_f32_e32 v43, v43, v179
	v_mul_f32_e32 v250, v250, v179
	v_mul_f32_e32 v44, v44, v179
	v_mul_f32_e32 v251, v251, v179
	v_mul_f32_e32 v45, v45, v179
	v_mul_f32_e32 v176, v176, v179
	v_mul_f32_e32 v46, v46, v179
	v_mul_f32_e32 v177, v177, v179
	v_mul_f32_e32 v47, v47, v179
	v_fmac_f32_e32 v238, v88, v246
	v_fmac_f32_e32 v48, v89, v40
	v_fmac_f32_e32 v239, v90, v247
	v_fmac_f32_e32 v49, v91, v41
	v_fmac_f32_e32 v240, v92, v248
	v_fmac_f32_e32 v50, v93, v42
	v_fmac_f32_e32 v241, v94, v249
	v_fmac_f32_e32 v51, v95, v43
	v_fmac_f32_e32 v242, v96, v250
	v_fmac_f32_e32 v52, v97, v44
	v_fmac_f32_e32 v243, v98, v251
	v_fmac_f32_e32 v53, v99, v45
	v_fmac_f32_e32 v244, v100, v176
	v_fmac_f32_e32 v54, v101, v46
	v_fmac_f32_e32 v245, v102, v177
	v_fmac_f32_e32 v55, v103, v47
	v_cvt_pk_bf16_f32 v120, v238, v48
	v_cvt_pk_bf16_f32 v121, v239, v49
	global_store_dwordx2 v2, v[120:121], s[4:5] offset:0 nt
	v_cvt_pk_bf16_f32 v122, v240, v50
	v_cvt_pk_bf16_f32 v123, v241, v51
	global_store_dwordx2 v2, v[122:123], s[4:5] offset:512 nt
	v_cvt_pk_bf16_f32 v124, v242, v52
	v_cvt_pk_bf16_f32 v125, v243, v53
	global_store_dwordx2 v2, v[124:125], s[4:5] offset:1024 nt
	v_cvt_pk_bf16_f32 v126, v244, v54
	v_cvt_pk_bf16_f32 v127, v245, v55
	global_store_dwordx2 v2, v[126:127], s[4:5] offset:1536 nt
	v_mul_f32_e32 v178, v238, v238
	v_fmac_f32_e32 v178, v48, v48
	v_fmac_f32_e32 v178, v239, v239
	v_fmac_f32_e32 v178, v49, v49
	v_fmac_f32_e32 v178, v240, v240
	v_fmac_f32_e32 v178, v50, v50
	v_fmac_f32_e32 v178, v241, v241
	v_fmac_f32_e32 v178, v51, v51
	v_fmac_f32_e32 v178, v242, v242
	v_fmac_f32_e32 v178, v52, v52
	v_fmac_f32_e32 v178, v243, v243
	v_fmac_f32_e32 v178, v53, v53
	v_fmac_f32_e32 v178, v244, v244
	v_fmac_f32_e32 v178, v54, v54
	v_fmac_f32_e32 v178, v245, v245
	v_fmac_f32_e32 v178, v55, v55
	s_nop 1
	v_add_f32_dpp v178, v178, v178 quad_perm:[1,0,3,2] row_mask:0xf bank_mask:0xf bound_ctrl:1
	s_nop 1
	v_add_f32_dpp v178, v178, v178 quad_perm:[2,3,0,1] row_mask:0xf bank_mask:0xf bound_ctrl:1
	s_nop 1
	v_add_f32_dpp v178, v178, v178 row_half_mirror row_mask:0xf bank_mask:0xf bound_ctrl:1
	s_nop 1
	v_add_f32_dpp v178, v178, v178 row_mirror row_mask:0xf bank_mask:0xf bound_ctrl:1
	s_nop 1
	v_add_f32_dpp v178, v178, v178 row_bcast:15 row_mask:0xa bank_mask:0xf
	s_nop 1
	v_add_f32_dpp v178, v178, v178 row_bcast:31 row_mask:0xc bank_mask:0xf
	s_nop 0
	v_readlane_b32 s0, v178, 63
	s_nop 1
	v_mov_b32_e32 v181, s0
	v_fmamk_f32 v181, v181, 0x3a800000, v161
	v_rsq_f32_e32 v180, v181
	s_nop 0
	v_mul_f32_e32 v238, v238, v180
	v_mul_f32_e32 v48, v48, v180
	v_mul_f32_e32 v239, v239, v180
	v_mul_f32_e32 v49, v49, v180
	v_mul_f32_e32 v240, v240, v180
	v_mul_f32_e32 v50, v50, v180
	v_mul_f32_e32 v241, v241, v180
	v_mul_f32_e32 v51, v51, v180
	v_mul_f32_e32 v242, v242, v180
	v_mul_f32_e32 v52, v52, v180
	v_mul_f32_e32 v243, v243, v180
	v_mul_f32_e32 v53, v53, v180
	v_mul_f32_e32 v244, v244, v180
	v_mul_f32_e32 v54, v54, v180
	v_mul_f32_e32 v245, v245, v180
	v_mul_f32_e32 v55, v55, v180
	v_fma_f32 v238, v238, v104, v134
	v_fma_f32 v48, v48, v105, v135
	v_fma_f32 v239, v239, v106, v136
	v_fma_f32 v49, v49, v107, v137
	v_fma_f32 v240, v240, v108, v138
	v_fma_f32 v50, v50, v109, v139
	v_fma_f32 v241, v241, v110, v140
	v_fma_f32 v51, v51, v111, v141
	v_fma_f32 v242, v242, v112, v142
	v_fma_f32 v52, v52, v113, v143
	v_fma_f32 v243, v243, v114, v144
	v_fma_f32 v53, v53, v115, v145
	v_fma_f32 v244, v244, v116, v146
	v_fma_f32 v54, v54, v117, v147
	v_fma_f32 v245, v245, v118, v148
	v_fma_f32 v55, v55, v119, v149
	v_cvt_pk_bf16_f32 v150, v238, v48
	v_cvt_pk_bf16_f32 v151, v239, v49
	global_store_dwordx2 v2, v[150:151], s[8:9] offset:0
	v_cvt_pk_bf16_f32 v152, v240, v50
	v_cvt_pk_bf16_f32 v153, v241, v51
	global_store_dwordx2 v2, v[152:153], s[8:9] offset:512
	v_cvt_pk_bf16_f32 v154, v242, v52
	v_cvt_pk_bf16_f32 v155, v243, v53
	global_store_dwordx2 v2, v[154:155], s[8:9] offset:1024
	v_cvt_pk_bf16_f32 v156, v244, v54
	v_cvt_pk_bf16_f32 v157, v245, v55
	global_store_dwordx2 v2, v[156:157], s[8:9] offset:1536
	s_waitcnt vmcnt(28)
	v_lshlrev_b32_e32 v246, 16, v8
	v_and_b32_e32 v8, 0xffff0000, v8
	v_lshlrev_b32_e32 v247, 16, v9
	v_and_b32_e32 v9, 0xffff0000, v9
	v_lshlrev_b32_e32 v248, 16, v10
	v_and_b32_e32 v10, 0xffff0000, v10
	v_lshlrev_b32_e32 v249, 16, v11
	v_and_b32_e32 v11, 0xffff0000, v11
	v_lshlrev_b32_e32 v250, 16, v12
	v_and_b32_e32 v12, 0xffff0000, v12
	v_lshlrev_b32_e32 v251, 16, v13
	v_and_b32_e32 v13, 0xffff0000, v13
	v_lshlrev_b32_e32 v176, 16, v14
	v_and_b32_e32 v14, 0xffff0000, v14
	v_lshlrev_b32_e32 v177, 16, v15
	v_and_b32_e32 v15, 0xffff0000, v15
	v_mul_f32_e32 v178, v246, v246
	v_fmac_f32_e32 v178, v8, v8
	v_fmac_f32_e32 v178, v247, v247
	v_fmac_f32_e32 v178, v9, v9
	v_fmac_f32_e32 v178, v248, v248
	v_fmac_f32_e32 v178, v10, v10
	v_fmac_f32_e32 v178, v249, v249
	v_fmac_f32_e32 v178, v11, v11
	v_fmac_f32_e32 v178, v250, v250
	v_fmac_f32_e32 v178, v12, v12
	v_fmac_f32_e32 v178, v251, v251
	v_fmac_f32_e32 v178, v13, v13
	v_fmac_f32_e32 v178, v176, v176
	v_fmac_f32_e32 v178, v14, v14
	v_fmac_f32_e32 v178, v177, v177
	v_fmac_f32_e32 v178, v15, v15
	s_waitcnt vmcnt(24)
	v_lshlrev_b32_e32 v238, 16, v16
	v_and_b32_e32 v16, 0xffff0000, v16
	v_add_f32_dpp v178, v178, v178 quad_perm:[1,0,3,2] row_mask:0xf bank_mask:0xf bound_ctrl:1
	v_lshlrev_b32_e32 v239, 16, v17
	v_and_b32_e32 v17, 0xffff0000, v17
	v_add_f32_dpp v178, v178, v178 quad_perm:[2,3,0,1] row_mask:0xf bank_mask:0xf bound_ctrl:1
	v_lshlrev_b32_e32 v240, 16, v18
	v_and_b32_e32 v18, 0xffff0000, v18
	v_add_f32_dpp v178, v178, v178 row_half_mirror row_mask:0xf bank_mask:0xf bound_ctrl:1
	v_lshlrev_b32_e32 v241, 16, v19
	v_and_b32_e32 v19, 0xffff0000, v19
	v_add_f32_dpp v178, v178, v178 row_mirror row_mask:0xf bank_mask:0xf bound_ctrl:1
	v_lshlrev_b32_e32 v242, 16, v20
	v_and_b32_e32 v20, 0xffff0000, v20
	v_add_f32_dpp v178, v178, v178 row_bcast:15 row_mask:0xa bank_mask:0xf
	v_lshlrev_b32_e32 v243, 16, v21
	v_and_b32_e32 v21, 0xffff0000, v21
	v_add_f32_dpp v178, v178, v178 row_bcast:31 row_mask:0xc bank_mask:0xf
	v_lshlrev_b32_e32 v244, 16, v22
	v_and_b32_e32 v22, 0xffff0000, v22
	v_lshlrev_b32_e32 v245, 16, v23
	v_and_b32_e32 v23, 0xffff0000, v23
	v_readlane_b32 s0, v178, 63
	s_nop 1
	v_mov_b32_e32 v181, s0
	v_fmamk_f32 v181, v181, 0x3a800000, v161
	v_rsq_f32_e32 v179, v181
	s_nop 0
	v_mul_f32_e32 v246, v246, v179
	v_mul_f32_e32 v8, v8, v179
	v_mul_f32_e32 v247, v247, v179
	v_mul_f32_e32 v9, v9, v179
	v_mul_f32_e32 v248, v248, v179
	v_mul_f32_e32 v10, v10, v179
	v_mul_f32_e32 v249, v249, v179
	v_mul_f32_e32 v11, v11, v179
	v_mul_f32_e32 v250, v250, v179
	v_mul_f32_e32 v12, v12, v179
	v_mul_f32_e32 v251, v251, v179
	v_mul_f32_e32 v13, v13, v179
	v_mul_f32_e32 v176, v176, v179
	v_mul_f32_e32 v14, v14, v179
	v_mul_f32_e32 v177, v177, v179
	v_mul_f32_e32 v15, v15, v179
	v_fmac_f32_e32 v238, v88, v246
	v_fmac_f32_e32 v16, v89, v8
	v_fmac_f32_e32 v239, v90, v247
	v_fmac_f32_e32 v17, v91, v9
	v_fmac_f32_e32 v240, v92, v248
	v_fmac_f32_e32 v18, v93, v10
	v_fmac_f32_e32 v241, v94, v249
	v_fmac_f32_e32 v19, v95, v11
	v_fmac_f32_e32 v242, v96, v250
	v_fmac_f32_e32 v20, v97, v12
	v_fmac_f32_e32 v243, v98, v251
	v_fmac_f32_e32 v21, v99, v13
	v_fmac_f32_e32 v244, v100, v176
	v_fmac_f32_e32 v22, v101, v14
	v_fmac_f32_e32 v245, v102, v177
	v_fmac_f32_e32 v23, v103, v15
	v_cvt_pk_bf16_f32 v120, v238, v16
	v_cvt_pk_bf16_f32 v121, v239, v17
	global_store_dwordx2 v3, v[120:121], s[4:5] offset:0 nt
	v_cvt_pk_bf16_f32 v122, v240, v18
	v_cvt_pk_bf16_f32 v123, v241, v19
	global_store_dwordx2 v3, v[122:123], s[4:5] offset:512 nt
	v_cvt_pk_bf16_f32 v124, v242, v20
	v_cvt_pk_bf16_f32 v125, v243, v21
	global_store_dwordx2 v3, v[124:125], s[4:5] offset:1024 nt
	v_cvt_pk_bf16_f32 v126, v244, v22
	v_cvt_pk_bf16_f32 v127, v245, v23
	global_store_dwordx2 v3, v[126:127], s[4:5] offset:1536 nt
	v_mul_f32_e32 v178, v238, v238
	v_fmac_f32_e32 v178, v16, v16
	v_fmac_f32_e32 v178, v239, v239
	v_fmac_f32_e32 v178, v17, v17
	v_fmac_f32_e32 v178, v240, v240
	v_fmac_f32_e32 v178, v18, v18
	v_fmac_f32_e32 v178, v241, v241
	v_fmac_f32_e32 v178, v19, v19
	v_fmac_f32_e32 v178, v242, v242
	v_fmac_f32_e32 v178, v20, v20
	v_fmac_f32_e32 v178, v243, v243
	v_fmac_f32_e32 v178, v21, v21
	v_fmac_f32_e32 v178, v244, v244
	v_fmac_f32_e32 v178, v22, v22
	v_fmac_f32_e32 v178, v245, v245
	v_fmac_f32_e32 v178, v23, v23
	s_nop 1
	v_add_f32_dpp v178, v178, v178 quad_perm:[1,0,3,2] row_mask:0xf bank_mask:0xf bound_ctrl:1
	s_nop 1
	v_add_f32_dpp v178, v178, v178 quad_perm:[2,3,0,1] row_mask:0xf bank_mask:0xf bound_ctrl:1
	s_nop 1
	v_add_f32_dpp v178, v178, v178 row_half_mirror row_mask:0xf bank_mask:0xf bound_ctrl:1
	s_nop 1
	v_add_f32_dpp v178, v178, v178 row_mirror row_mask:0xf bank_mask:0xf bound_ctrl:1
	s_nop 1
	v_add_f32_dpp v178, v178, v178 row_bcast:15 row_mask:0xa bank_mask:0xf
	s_nop 1
	v_add_f32_dpp v178, v178, v178 row_bcast:31 row_mask:0xc bank_mask:0xf
	s_nop 0
	v_readlane_b32 s0, v178, 63
	s_nop 1
	v_mov_b32_e32 v181, s0
	v_fmamk_f32 v181, v181, 0x3a800000, v161
	v_rsq_f32_e32 v180, v181
	s_nop 0
	v_mul_f32_e32 v238, v238, v180
	v_mul_f32_e32 v16, v16, v180
	v_mul_f32_e32 v239, v239, v180
	v_mul_f32_e32 v17, v17, v180
	v_mul_f32_e32 v240, v240, v180
	v_mul_f32_e32 v18, v18, v180
	v_mul_f32_e32 v241, v241, v180
	v_mul_f32_e32 v19, v19, v180
	v_mul_f32_e32 v242, v242, v180
	v_mul_f32_e32 v20, v20, v180
	v_mul_f32_e32 v243, v243, v180
	v_mul_f32_e32 v21, v21, v180
	v_mul_f32_e32 v244, v244, v180
	v_mul_f32_e32 v22, v22, v180
	v_mul_f32_e32 v245, v245, v180
	v_mul_f32_e32 v23, v23, v180
	v_fma_f32 v238, v238, v104, v134
	v_fma_f32 v16, v16, v105, v135
	v_fma_f32 v239, v239, v106, v136
	v_fma_f32 v17, v17, v107, v137
	v_fma_f32 v240, v240, v108, v138
	v_fma_f32 v18, v18, v109, v139
	v_fma_f32 v241, v241, v110, v140
	v_fma_f32 v19, v19, v111, v141
	v_fma_f32 v242, v242, v112, v142
	v_fma_f32 v20, v20, v113, v143
	v_fma_f32 v243, v243, v114, v144
	v_fma_f32 v21, v21, v115, v145
	v_fma_f32 v244, v244, v116, v146
	v_fma_f32 v22, v22, v117, v147
	v_fma_f32 v245, v245, v118, v148
	v_fma_f32 v23, v23, v119, v149
	v_cvt_pk_bf16_f32 v150, v238, v16
	v_cvt_pk_bf16_f32 v151, v239, v17
	global_store_dwordx2 v3, v[150:151], s[8:9] offset:0
	v_cvt_pk_bf16_f32 v152, v240, v18
	v_cvt_pk_bf16_f32 v153, v241, v19
	global_store_dwordx2 v3, v[152:153], s[8:9] offset:512
	v_cvt_pk_bf16_f32 v154, v242, v20
	v_cvt_pk_bf16_f32 v155, v243, v21
	global_store_dwordx2 v3, v[154:155], s[8:9] offset:1024
	v_cvt_pk_bf16_f32 v156, v244, v22
	v_cvt_pk_bf16_f32 v157, v245, v23
	global_store_dwordx2 v3, v[156:157], s[8:9] offset:1536
	s_waitcnt vmcnt(28)
	v_lshlrev_b32_e32 v246, 16, v190
	v_and_b32_e32 v190, 0xffff0000, v190
	v_lshlrev_b32_e32 v247, 16, v191
	v_and_b32_e32 v191, 0xffff0000, v191
	v_lshlrev_b32_e32 v248, 16, v192
	v_and_b32_e32 v192, 0xffff0000, v192
	v_lshlrev_b32_e32 v249, 16, v193
	v_and_b32_e32 v193, 0xffff0000, v193
	v_lshlrev_b32_e32 v250, 16, v194
	v_and_b32_e32 v194, 0xffff0000, v194
	v_lshlrev_b32_e32 v251, 16, v195
	v_and_b32_e32 v195, 0xffff0000, v195
	v_lshlrev_b32_e32 v176, 16, v196
	v_and_b32_e32 v196, 0xffff0000, v196
	v_lshlrev_b32_e32 v177, 16, v197
	v_and_b32_e32 v197, 0xffff0000, v197
	v_mul_f32_e32 v178, v246, v246
	v_fmac_f32_e32 v178, v190, v190
	v_fmac_f32_e32 v178, v247, v247
	v_fmac_f32_e32 v178, v191, v191
	v_fmac_f32_e32 v178, v248, v248
	v_fmac_f32_e32 v178, v192, v192
	v_fmac_f32_e32 v178, v249, v249
	v_fmac_f32_e32 v178, v193, v193
	v_fmac_f32_e32 v178, v250, v250
	v_fmac_f32_e32 v178, v194, v194
	v_fmac_f32_e32 v178, v251, v251
	v_fmac_f32_e32 v178, v195, v195
	v_fmac_f32_e32 v178, v176, v176
	v_fmac_f32_e32 v178, v196, v196
	v_fmac_f32_e32 v178, v177, v177
	v_fmac_f32_e32 v178, v197, v197
	s_waitcnt vmcnt(24)
	v_lshlrev_b32_e32 v238, 16, v198
	v_and_b32_e32 v198, 0xffff0000, v198
	v_add_f32_dpp v178, v178, v178 quad_perm:[1,0,3,2] row_mask:0xf bank_mask:0xf bound_ctrl:1
	v_lshlrev_b32_e32 v239, 16, v199
	v_and_b32_e32 v199, 0xffff0000, v199
	v_add_f32_dpp v178, v178, v178 quad_perm:[2,3,0,1] row_mask:0xf bank_mask:0xf bound_ctrl:1
	v_lshlrev_b32_e32 v240, 16, v200
	v_and_b32_e32 v200, 0xffff0000, v200
	v_add_f32_dpp v178, v178, v178 row_half_mirror row_mask:0xf bank_mask:0xf bound_ctrl:1
	v_lshlrev_b32_e32 v241, 16, v201
	v_and_b32_e32 v201, 0xffff0000, v201
	v_add_f32_dpp v178, v178, v178 row_mirror row_mask:0xf bank_mask:0xf bound_ctrl:1
	v_lshlrev_b32_e32 v242, 16, v202
	v_and_b32_e32 v202, 0xffff0000, v202
	v_add_f32_dpp v178, v178, v178 row_bcast:15 row_mask:0xa bank_mask:0xf
	v_lshlrev_b32_e32 v243, 16, v203
	v_and_b32_e32 v203, 0xffff0000, v203
	v_add_f32_dpp v178, v178, v178 row_bcast:31 row_mask:0xc bank_mask:0xf
	v_lshlrev_b32_e32 v244, 16, v204
	v_and_b32_e32 v204, 0xffff0000, v204
	v_lshlrev_b32_e32 v245, 16, v205
	v_and_b32_e32 v205, 0xffff0000, v205
	v_readlane_b32 s0, v178, 63
	s_nop 1
	v_mov_b32_e32 v181, s0
	v_fmamk_f32 v181, v181, 0x3a800000, v161
	v_rsq_f32_e32 v179, v181
	s_nop 0
	v_mul_f32_e32 v246, v246, v179
	v_mul_f32_e32 v190, v190, v179
	v_mul_f32_e32 v247, v247, v179
	v_mul_f32_e32 v191, v191, v179
	v_mul_f32_e32 v248, v248, v179
	v_mul_f32_e32 v192, v192, v179
	v_mul_f32_e32 v249, v249, v179
	v_mul_f32_e32 v193, v193, v179
	v_mul_f32_e32 v250, v250, v179
	v_mul_f32_e32 v194, v194, v179
	v_mul_f32_e32 v251, v251, v179
	v_mul_f32_e32 v195, v195, v179
	v_mul_f32_e32 v176, v176, v179
	v_mul_f32_e32 v196, v196, v179
	v_mul_f32_e32 v177, v177, v179
	v_mul_f32_e32 v197, v197, v179
	v_fmac_f32_e32 v238, v88, v246
	v_fmac_f32_e32 v198, v89, v190
	v_fmac_f32_e32 v239, v90, v247
	v_fmac_f32_e32 v199, v91, v191
	v_fmac_f32_e32 v240, v92, v248
	v_fmac_f32_e32 v200, v93, v192
	v_fmac_f32_e32 v241, v94, v249
	v_fmac_f32_e32 v201, v95, v193
	v_fmac_f32_e32 v242, v96, v250
	v_fmac_f32_e32 v202, v97, v194
	v_fmac_f32_e32 v243, v98, v251
	v_fmac_f32_e32 v203, v99, v195
	v_fmac_f32_e32 v244, v100, v176
	v_fmac_f32_e32 v204, v101, v196
	v_fmac_f32_e32 v245, v102, v177
	v_fmac_f32_e32 v205, v103, v197
	v_cvt_pk_bf16_f32 v120, v238, v198
	v_cvt_pk_bf16_f32 v121, v239, v199
	global_store_dwordx2 v4, v[120:121], s[4:5] offset:0 nt
	v_cvt_pk_bf16_f32 v122, v240, v200
	v_cvt_pk_bf16_f32 v123, v241, v201
	global_store_dwordx2 v4, v[122:123], s[4:5] offset:512 nt
	v_cvt_pk_bf16_f32 v124, v242, v202
	v_cvt_pk_bf16_f32 v125, v243, v203
	global_store_dwordx2 v4, v[124:125], s[4:5] offset:1024 nt
	v_cvt_pk_bf16_f32 v126, v244, v204
	v_cvt_pk_bf16_f32 v127, v245, v205
	global_store_dwordx2 v4, v[126:127], s[4:5] offset:1536 nt
	v_mul_f32_e32 v178, v238, v238
	v_fmac_f32_e32 v178, v198, v198
	v_fmac_f32_e32 v178, v239, v239
	v_fmac_f32_e32 v178, v199, v199
	v_fmac_f32_e32 v178, v240, v240
	v_fmac_f32_e32 v178, v200, v200
	v_fmac_f32_e32 v178, v241, v241
	v_fmac_f32_e32 v178, v201, v201
	v_fmac_f32_e32 v178, v242, v242
	v_fmac_f32_e32 v178, v202, v202
	v_fmac_f32_e32 v178, v243, v243
	v_fmac_f32_e32 v178, v203, v203
	v_fmac_f32_e32 v178, v244, v244
	v_fmac_f32_e32 v178, v204, v204
	v_fmac_f32_e32 v178, v245, v245
	v_fmac_f32_e32 v178, v205, v205
	s_nop 1
	v_add_f32_dpp v178, v178, v178 quad_perm:[1,0,3,2] row_mask:0xf bank_mask:0xf bound_ctrl:1
	s_nop 1
	v_add_f32_dpp v178, v178, v178 quad_perm:[2,3,0,1] row_mask:0xf bank_mask:0xf bound_ctrl:1
	s_nop 1
	v_add_f32_dpp v178, v178, v178 row_half_mirror row_mask:0xf bank_mask:0xf bound_ctrl:1
	s_nop 1
	v_add_f32_dpp v178, v178, v178 row_mirror row_mask:0xf bank_mask:0xf bound_ctrl:1
	s_nop 1
	v_add_f32_dpp v178, v178, v178 row_bcast:15 row_mask:0xa bank_mask:0xf
	s_nop 1
	v_add_f32_dpp v178, v178, v178 row_bcast:31 row_mask:0xc bank_mask:0xf
	s_nop 0
	v_readlane_b32 s0, v178, 63
	s_nop 1
	v_mov_b32_e32 v181, s0
	v_fmamk_f32 v181, v181, 0x3a800000, v161
	v_rsq_f32_e32 v180, v181
	s_nop 0
	v_mul_f32_e32 v238, v238, v180
	v_mul_f32_e32 v198, v198, v180
	v_mul_f32_e32 v239, v239, v180
	v_mul_f32_e32 v199, v199, v180
	v_mul_f32_e32 v240, v240, v180
	v_mul_f32_e32 v200, v200, v180
	v_mul_f32_e32 v241, v241, v180
	v_mul_f32_e32 v201, v201, v180
	v_mul_f32_e32 v242, v242, v180
	v_mul_f32_e32 v202, v202, v180
	v_mul_f32_e32 v243, v243, v180
	v_mul_f32_e32 v203, v203, v180
	v_mul_f32_e32 v244, v244, v180
	v_mul_f32_e32 v204, v204, v180
	v_mul_f32_e32 v245, v245, v180
	v_mul_f32_e32 v205, v205, v180
	v_fma_f32 v238, v238, v104, v134
	v_fma_f32 v198, v198, v105, v135
	v_fma_f32 v239, v239, v106, v136
	v_fma_f32 v199, v199, v107, v137
	v_fma_f32 v240, v240, v108, v138
	v_fma_f32 v200, v200, v109, v139
	v_fma_f32 v241, v241, v110, v140
	v_fma_f32 v201, v201, v111, v141
	v_fma_f32 v242, v242, v112, v142
	v_fma_f32 v202, v202, v113, v143
	v_fma_f32 v243, v243, v114, v144
	v_fma_f32 v203, v203, v115, v145
	v_fma_f32 v244, v244, v116, v146
	v_fma_f32 v204, v204, v117, v147
	v_fma_f32 v245, v245, v118, v148
	v_fma_f32 v205, v205, v119, v149
	v_cvt_pk_bf16_f32 v150, v238, v198
	v_cvt_pk_bf16_f32 v151, v239, v199
	global_store_dwordx2 v4, v[150:151], s[8:9] offset:0
	v_cvt_pk_bf16_f32 v152, v240, v200
	v_cvt_pk_bf16_f32 v153, v241, v201
	global_store_dwordx2 v4, v[152:153], s[8:9] offset:512
	v_cvt_pk_bf16_f32 v154, v242, v202
	v_cvt_pk_bf16_f32 v155, v243, v203
	global_store_dwordx2 v4, v[154:155], s[8:9] offset:1024
	v_cvt_pk_bf16_f32 v156, v244, v204
	v_cvt_pk_bf16_f32 v157, v245, v205
	global_store_dwordx2 v4, v[156:157], s[8:9] offset:1536
	s_mov_b64 s[0:1], 0
	s_branch .LBB0_190
